# speedup vs baseline: 1.0242x; 1.0242x over previous
; __device__ __forceinline__ void phase_B(const Params& p, int l) {
;     const int G = gridDim.x, bid = blockIdx.x;
;     const int nPool = (G * 64) >> 8, nConv = (G * 104) >> 8, nAttn = G - nPool - nConv;
;     if (bid < nPool) {
;         for (int it = bid; it < 256; it += nPool) pool_item(p, l, it);
;     } else if (bid < nPool + nConv) {
;         for (int it = bid - nPool; it < 512; it += nConv) conv_item(p, l, it);
;     } else {
;         for (int ai = bid - nPool - nConv; ai < 512; ai += nAttn) attn_block(p, ai >> 5, ai & 31);
; __global__ void __launch_bounds__(512, 2) mega(Params p) {
;     ...
; #pragma unroll 1
;     for (int l = 0; l < 2; ++l) {
;         const unsigned e0 = 1u + 5u * (unsigned)l;
;         phase_A(p, l);
.LBB0_76:
	s_or_b64 exec, exec, s[0:1]
	s_load_dwordx8 s[40:47], s[52:53], 0x68
	s_load_dwordx8 s[4:11], s[52:53], 0x0
	s_load_dwordx8 s[56:63], s[52:53], 0x38
	s_movk_i32 s91, 0x100
	v_mov_b32_e32 v129, 0
	s_waitcnt lgkmcnt(0)
	s_add_u32 s74, s46, 0x1430000
	s_addc_u32 s75, s47, 0
	s_add_u32 s76, s46, 0x10000
	s_addc_u32 s77, s47, 0
	s_add_u32 s78, s46, 0x3430000
	s_addc_u32 s79, s47, 0
	s_add_u32 s0, s46, 0xb430000
	s_addc_u32 s1, s47, 0
	v_writelane_b32 v234, s0, 4
	s_cmpk_lt_i32 s50, 0x780
	s_movk_i32 s81, 0x3c0
	v_writelane_b32 v234, s1, 5
	s_cselect_b64 s[0:1], -1, 0
	v_writelane_b32 v234, s0, 6
	s_movk_i32 s55, 0xc00
	v_mov_b32_e32 v209, 0x43008000
	v_writelane_b32 v234, s1, 7
	s_add_i32 s0, s50, 0x1e0
	v_writelane_b32 v234, s0, 8
	s_add_u32 s0, s46, 0xf10000
	v_writelane_b32 v234, s0, 9
	s_addc_u32 s0, s47, 0
	s_add_u32 s84, s46, 0x1230000
	s_addc_u32 s85, s47, 0
	v_writelane_b32 v234, s0, 10
	s_add_u32 s33, s46, 0xf30000
	s_mul_i32 s0, s54, 0x56
	s_addc_u32 s68, s47, 0
	s_ashr_i32 s2, s54, 2
	s_ashr_i32 s3, s0, 8
	s_add_i32 s0, s3, s2
	s_sub_i32 s1, s54, s0
	s_cmp_ge_i32 s50, s2
	v_writelane_b32 v234, s1, 11
	s_cselect_b64 s[12:13], -1, 0
	v_writelane_b32 v234, s12, 12
	s_cmp_ge_i32 s50, s0
	v_mov_b32_e32 v210, 1
	v_writelane_b32 v234, s13, 13
	s_cselect_b64 s[12:13], -1, 0
	v_writelane_b32 v234, s12, 14
	s_sub_i32 s0, s50, s0
	s_cmpk_lt_i32 s0, 0x200
	v_writelane_b32 v234, s13, 15
	v_writelane_b32 v234, s0, 16
	s_cselect_b64 s[0:1], -1, 0
	v_writelane_b32 v234, s0, 17
	v_mov_b32_e32 v211, 0x358637bd
	v_mov_b32_e32 v212, 0x437f0000
	v_writelane_b32 v234, s1, 18
	s_sub_i32 s0, s50, s2
	s_cmpk_lt_i32 s0, 0x200
	v_writelane_b32 v234, s0, 19
	s_cselect_b64 s[0:1], -1, 0
	v_writelane_b32 v234, s0, 20
	s_cmpk_lt_i32 s50, 0x100
	v_mbcnt_hi_u32_b32 v213, -1, v132
	v_writelane_b32 v234, s1, 21
	s_cselect_b64 s[0:1], -1, 0
	v_writelane_b32 v234, s0, 22
	s_mov_b32 s69, 0x80000
	s_mov_b32 s94, 0x800000
	v_writelane_b32 v234, s1, 23
	s_add_u32 s0, s46, 0xc530000
	v_writelane_b32 v234, s0, 24
	s_addc_u32 s0, s47, 0
	s_add_u32 s96, s46, 0xc430000
	s_addc_u32 s97, s47, 0
	v_writelane_b32 v234, s0, 25
	s_add_u32 s0, s6, 0x1000
	s_addc_u32 s1, s7, 0
	v_writelane_b32 v234, s0, 26
	s_add_u32 s12, s8, 0x1e00000
	s_addc_u32 s13, s9, 0
	v_writelane_b32 v234, s1, 27
	s_mov_b64 s[0:1], s[4:5]
	s_mov_b64 s[4:5], s[8:9]
	s_mov_b64 s[6:7], s[10:11]
	v_writelane_b32 v234, s0, 28
	s_add_u32 s65, s46, 0x1470000
	s_addc_u32 s66, s47, 0
	v_writelane_b32 v234, s1, 29
	v_writelane_b32 v234, s2, 30
	v_writelane_b32 v234, s3, 31
	v_writelane_b32 v234, s4, 32
	v_writelane_b32 v234, s5, 33
	v_writelane_b32 v234, s6, 34
	v_writelane_b32 v234, s7, 35
	v_writelane_b32 v234, s12, 36
	s_lshl_b32 s1, s50, 5
	s_lshl_b32 s0, s2, 5
	v_writelane_b32 v234, s13, 37
	v_writelane_b32 v234, s2, 38
	v_writelane_b32 v234, s1, 39
	s_sub_i32 s0, s1, s0
	v_writelane_b32 v234, s0, 40
	v_writelane_b32 v234, s3, 41
	s_lshl_b32 s0, s3, 5
	v_writelane_b32 v234, s0, 42
	s_add_u32 s0, s46, 0x3530000
	v_writelane_b32 v234, s0, 43
	s_addc_u32 s0, s47, 0
	v_writelane_b32 v234, s0, 44
	s_lshl_b32 s0, s54, 5
	v_writelane_b32 v234, s0, 45
	s_mov_b32 s0, 0
	v_writelane_b32 v234, s0, 46
	s_mov_b64 s[0:1], -1
	v_writelane_b32 v234, s0, 47
	s_add_i32 s90, 0, 0x10000
	s_add_i32 s64, 0, 0x14000
	v_writelane_b32 v234, s1, 48
	s_load_dwordx4 s[0:3], s[52:53], 0x20
	s_add_i32 s67, 0, 0x18000
	s_add_i32 s80, 0, 0x1c000
	s_movk_i32 s95, 0xe400
	s_movk_i32 s70, 0x7800
	s_waitcnt lgkmcnt(0)
	v_writelane_b32 v234, s0, 49
	s_mov_b64 s[88:89], 0x40000
	s_mov_b64 s[82:83], 0x20000
	v_writelane_b32 v234, s1, 50
	v_writelane_b32 v234, s2, 51
	v_writelane_b32 v234, s3, 52
	v_writelane_b32 v234, s50, 53
	v_writelane_b32 v234, s52, 54
	s_mov_b64 s[86:87], 0x60000
	s_mov_b64 s[48:49], 0x400
	v_writelane_b32 v234, s53, 55
	v_writelane_b32 v234, s92, 56
	s_barrier
	s_nop 0
	v_writelane_b32 v234, s93, 57
	v_writelane_b32 v234, s51, 58
	v_writelane_b32 v234, s54, 59
	s_branch .LBB0_80

; __device__ __forceinline__ void conv_item(const Params& p, int l, int item) {
;     ...
;         const int c = tid;
;         float wj[31];
; #pragma unroll
;         for (int j = 0; j < 31; ++j) wj[j] = p.conv_w[(l * 31 + j) * 512 + c];
;         const float bias = p.conv_b[l * 512 + c];
;         float win[62];
; #pragma unroll
;         for (int i = 0; i < 62; ++i) win[i] = __builtin_bit_cast(float, (unsigned)U[i * 512 + c] << 16);
.LBB0_170:
	s_or_b64 exec, exec, s[0:1]
	s_waitcnt vmcnt(0)
	v_add_u32_e32 v4, s2, v30
	v_ashrrev_i32_e32 v5, 31, v4
	v_lshl_add_u64 v[8:9], v[4:5], 2, s[56:57]
	v_add_u32_e32 v4, s2, v31
	v_ashrrev_i32_e32 v5, 31, v4
	v_lshl_add_u64 v[10:11], v[4:5], 2, s[56:57]
	v_add_u32_e32 v4, s2, v32
	v_ashrrev_i32_e32 v5, 31, v4
	v_add_u32_e32 v24, s2, v29
	v_lshl_add_u64 v[12:13], v[4:5], 2, s[56:57]
	v_add_u32_e32 v4, s2, v33
	v_add_u32_e32 v2, 0x400, v24
	v_ashrrev_i32_e32 v5, 31, v4
	v_ashrrev_i32_e32 v25, 31, v24
	v_ashrrev_i32_e32 v3, 31, v2
	v_lshl_add_u64 v[14:15], v[4:5], 2, s[56:57]
	v_add_u32_e32 v4, s2, v34
	v_lshl_add_u64 v[0:1], v[24:25], 2, s[56:57]
	v_lshl_add_u64 v[2:3], v[2:3], 2, s[56:57]
	v_ashrrev_i32_e32 v5, 31, v4
	s_waitcnt lgkmcnt(0)
	s_barrier
	v_lshl_add_u64 v[16:17], v[4:5], 2, s[56:57]
	global_load_dword v7, v[0:1], off
	global_load_dword v6, v[0:1], off offset:2048
	global_load_dword v5, v[2:3], off
	global_load_dword v4, v[8:9], off
	s_nop 0
	global_load_dword v3, v[10:11], off
	global_load_dword v2, v[12:13], off
	global_load_dword v1, v[14:15], off
	global_load_dword v0, v[16:17], off
	v_add_u32_e32 v14, 0x1600, v24
	v_ashrrev_i32_e32 v15, 31, v14
	v_lshl_add_u64 v[16:17], v[14:15], 2, s[56:57]
	v_add_u32_e32 v14, 0x1800, v24
	v_ashrrev_i32_e32 v15, 31, v14
	v_lshl_add_u64 v[18:19], v[14:15], 2, s[56:57]
	v_add_u32_e32 v14, 0x1a00, v24
	v_ashrrev_i32_e32 v15, 31, v14
	v_lshl_add_u64 v[20:21], v[14:15], 2, s[56:57]
	v_add_u32_e32 v14, 0x1c00, v24
	v_add_u32_e32 v8, 0x1000, v24
	v_add_u32_e32 v10, 0x1200, v24
	v_add_u32_e32 v12, 0x1400, v24
	v_ashrrev_i32_e32 v15, 31, v14
	v_ashrrev_i32_e32 v9, 31, v8
	v_ashrrev_i32_e32 v11, 31, v10
	v_ashrrev_i32_e32 v13, 31, v12
	v_lshl_add_u64 v[22:23], v[14:15], 2, s[56:57]
	v_add_u32_e32 v14, 0x1e00, v24
	v_lshl_add_u64 v[8:9], v[8:9], 2, s[56:57]
	v_lshl_add_u64 v[10:11], v[10:11], 2, s[56:57]
	v_lshl_add_u64 v[12:13], v[12:13], 2, s[56:57]
	v_ashrrev_i32_e32 v15, 31, v14
	v_lshl_add_u64 v[26:27], v[14:15], 2, s[56:57]
	global_load_dword v15, v[8:9], off
	global_load_dword v14, v[10:11], off
	s_nop 0
	global_load_dword v13, v[12:13], off
	s_nop 0
	global_load_dword v12, v[16:17], off
	global_load_dword v11, v[18:19], off
	global_load_dword v10, v[20:21], off
	global_load_dword v9, v[22:23], off
	global_load_dword v8, v[26:27], off
	v_add_u32_e32 v22, 0x2600, v24
	v_ashrrev_i32_e32 v23, 31, v22
	v_lshl_add_u64 v[26:27], v[22:23], 2, s[56:57]
	v_add_u32_e32 v22, 0x2800, v24
	v_ashrrev_i32_e32 v23, 31, v22
	v_lshl_add_u64 v[30:31], v[22:23], 2, s[56:57]
	v_add_u32_e32 v22, 0x2a00, v24
	v_ashrrev_i32_e32 v23, 31, v22
	v_lshl_add_u64 v[32:33], v[22:23], 2, s[56:57]
	v_add_u32_e32 v22, 0x2c00, v24
	v_add_u32_e32 v16, 0x2000, v24
	v_add_u32_e32 v18, 0x2200, v24
	v_add_u32_e32 v20, 0x2400, v24
	v_ashrrev_i32_e32 v23, 31, v22
	v_ashrrev_i32_e32 v17, 31, v16
	v_ashrrev_i32_e32 v19, 31, v18
	v_ashrrev_i32_e32 v21, 31, v20
	v_lshl_add_u64 v[34:35], v[22:23], 2, s[56:57]
	v_add_u32_e32 v22, 0x2e00, v24
	v_lshl_add_u64 v[16:17], v[16:17], 2, s[56:57]
	v_lshl_add_u64 v[18:19], v[18:19], 2, s[56:57]
	v_lshl_add_u64 v[20:21], v[20:21], 2, s[56:57]
	v_ashrrev_i32_e32 v23, 31, v22
	v_lshl_add_u64 v[36:37], v[22:23], 2, s[56:57]
	global_load_dword v23, v[16:17], off
	global_load_dword v22, v[18:19], off
	s_nop 0
	global_load_dword v21, v[20:21], off
	s_nop 0
	global_load_dword v20, v[26:27], off
	global_load_dword v19, v[30:31], off
	global_load_dword v18, v[32:33], off
	global_load_dword v17, v[34:35], off
	global_load_dword v16, v[36:37], off
	v_add_u32_e32 v32, 0x3400, v24
	v_ashrrev_i32_e32 v33, 31, v32
	v_lshl_add_u64 v[34:35], v[32:33], 2, s[56:57]
	v_add_u32_e32 v32, 0x3600, v24
	v_ashrrev_i32_e32 v33, 31, v32
	v_lshl_add_u64 v[36:37], v[32:33], 2, s[56:57]
	v_add_u32_e32 v32, 0x3800, v24
	v_add_u32_e32 v26, 0x3000, v24
	v_add_u32_e32 v30, 0x3200, v24
	v_ashrrev_i32_e32 v33, 31, v32
	v_ashrrev_i32_e32 v27, 31, v26
	v_ashrrev_i32_e32 v31, 31, v30
	v_lshl_add_u64 v[38:39], v[32:33], 2, s[56:57]
	v_add_u32_e32 v32, 0x3a00, v24
	v_add_u32_e32 v24, 0x3c00, v24
	v_lshl_add_u64 v[26:27], v[26:27], 2, s[56:57]
	v_lshl_add_u64 v[30:31], v[30:31], 2, s[56:57]
	v_ashrrev_i32_e32 v33, 31, v32
	v_ashrrev_i32_e32 v25, 31, v24
	v_lshl_add_u64 v[40:41], v[32:33], 2, s[56:57]
	v_lshl_add_u64 v[42:43], v[24:25], 2, s[56:57]
	global_load_dword v33, v[26:27], off
	s_nop 0
	global_load_dword v31, v[30:31], off
	s_nop 0
	global_load_dword v30, v[34:35], off
	global_load_dword v27, v[36:37], off
	global_load_dword v26, v[38:39], off
	global_load_dword v25, v[40:41], off
	global_load_dword v24, v[42:43], off
	v_add_u32_e32 v34, s72, v29
	v_ashrrev_i32_e32 v35, 31, v34
	v_lshl_add_u64 v[34:35], v[34:35], 2, s[58:59]
	global_load_dword v32, v[34:35], off
	v_lshl_add_u32 v34, v29, 1, 0
	ds_read_u16 v35, v34
	ds_read_u16 v36, v34 offset:1024
	ds_read_u16 v37, v34 offset:57344
	ds_read_u16 v38, v34 offset:58368
	ds_read_u16 v90, v34 offset:59392
	ds_read_u16 v91, v34 offset:60416
	ds_read_u16 v92, v34 offset:61440
	ds_read_u16 v93, v34 offset:62464
	s_waitcnt lgkmcnt(7)
	v_lshlrev_b32_e32 v94, 16, v35
	s_waitcnt lgkmcnt(6)
	v_lshlrev_b32_e32 v95, 16, v36
	ds_read_u16 v35, v34 offset:2048
	ds_read_u16 v36, v34 offset:3072
	ds_read_u16 v39, v34 offset:4096
	ds_read_u16 v40, v34 offset:5120
	ds_read_u16 v41, v34 offset:6144
	ds_read_u16 v42, v34 offset:7168
	ds_read_u16 v43, v34 offset:8192
	ds_read_u16 v44, v34 offset:9216
	s_waitcnt lgkmcnt(7)
	v_lshlrev_b32_e32 v96, 16, v35
	s_waitcnt lgkmcnt(6)
	v_lshlrev_b32_e32 v97, 16, v36
	s_waitcnt lgkmcnt(5)
	v_lshlrev_b32_e32 v98, 16, v39
	s_waitcnt lgkmcnt(4)
; __device__ __forceinline__ void conv_item(const Params& p, int l, int item) {
;     ...
;         float win[62];
; #pragma unroll
;         for (int i = 0; i < 62; ++i) win[i] = __builtin_bit_cast(float, (unsigned)U[i * 512 + c] << 16);
	v_lshlrev_b32_e32 v99, 16, v40
	s_waitcnt lgkmcnt(3)
	v_lshlrev_b32_e32 v100, 16, v41
	s_waitcnt lgkmcnt(2)
	v_lshlrev_b32_e32 v89, 16, v42
	s_waitcnt lgkmcnt(1)
	v_lshlrev_b32_e32 v88, 16, v43
	s_waitcnt lgkmcnt(0)
	v_lshlrev_b32_e32 v87, 16, v44
	ds_read_u16 v35, v34 offset:10240
	ds_read_u16 v36, v34 offset:11264
	ds_read_u16 v39, v34 offset:12288
	ds_read_u16 v40, v34 offset:13312
	ds_read_u16 v41, v34 offset:14336
	ds_read_u16 v42, v34 offset:15360
	ds_read_u16 v43, v34 offset:16384
	ds_read_u16 v44, v34 offset:17408
	s_waitcnt lgkmcnt(7)
	v_lshlrev_b32_e32 v86, 16, v35
	s_waitcnt lgkmcnt(6)
	v_lshlrev_b32_e32 v85, 16, v36
	s_waitcnt lgkmcnt(5)
	v_lshlrev_b32_e32 v84, 16, v39
	s_waitcnt lgkmcnt(4)
	v_lshlrev_b32_e32 v83, 16, v40
	s_waitcnt lgkmcnt(3)
	v_lshlrev_b32_e32 v82, 16, v41
	s_waitcnt lgkmcnt(2)
	v_lshlrev_b32_e32 v81, 16, v42
	s_waitcnt lgkmcnt(1)
	v_lshlrev_b32_e32 v80, 16, v43
	s_waitcnt lgkmcnt(0)
	v_lshlrev_b32_e32 v79, 16, v44
	ds_read_u16 v35, v34 offset:18432
	ds_read_u16 v36, v34 offset:19456
	ds_read_u16 v39, v34 offset:20480
	ds_read_u16 v40, v34 offset:21504
	ds_read_u16 v41, v34 offset:22528
	ds_read_u16 v42, v34 offset:23552
	ds_read_u16 v43, v34 offset:24576
	ds_read_u16 v44, v34 offset:25600
	s_waitcnt lgkmcnt(7)
	v_lshlrev_b32_e32 v78, 16, v35
	s_waitcnt lgkmcnt(6)
	v_lshlrev_b32_e32 v77, 16, v36
	s_waitcnt lgkmcnt(5)
	v_lshlrev_b32_e32 v76, 16, v39
	s_waitcnt lgkmcnt(4)
	v_lshlrev_b32_e32 v75, 16, v40
	s_waitcnt lgkmcnt(3)
	v_lshlrev_b32_e32 v74, 16, v41
	s_waitcnt lgkmcnt(2)
	v_lshlrev_b32_e32 v73, 16, v42
	ds_read_u16 v35, v34 offset:26624
	ds_read_u16 v36, v34 offset:27648
	ds_read_u16 v39, v34 offset:28672
	ds_read_u16 v40, v34 offset:29696
	ds_read_u16 v41, v34 offset:30720
	ds_read_u16 v42, v34 offset:31744
	s_waitcnt lgkmcnt(7)
	v_lshlrev_b32_e32 v72, 16, v43
	s_waitcnt lgkmcnt(6)
	v_lshlrev_b32_e32 v71, 16, v44
	s_waitcnt lgkmcnt(5)
	v_lshlrev_b32_e32 v70, 16, v35
	s_waitcnt lgkmcnt(4)
	v_lshlrev_b32_e32 v69, 16, v36
	s_waitcnt lgkmcnt(3)
	v_lshlrev_b32_e32 v68, 16, v39
	s_waitcnt lgkmcnt(2)
	v_lshlrev_b32_e32 v67, 16, v40
	s_waitcnt lgkmcnt(1)
	v_lshlrev_b32_e32 v66, 16, v41
	s_waitcnt lgkmcnt(0)
	v_lshlrev_b32_e32 v41, 16, v42
	ds_read_u16 v35, v34 offset:32768
	ds_read_u16 v36, v34 offset:33792
	ds_read_u16 v39, v34 offset:34816
	ds_read_u16 v40, v34 offset:35840
	ds_read_u16 v42, v34 offset:36864
	ds_read_u16 v43, v34 offset:37888
	ds_read_u16 v44, v34 offset:38912
	ds_read_u16 v46, v34 offset:39936
	s_waitcnt lgkmcnt(7)
	v_lshlrev_b32_e32 v63, 16, v35
	s_waitcnt lgkmcnt(6)
	v_lshlrev_b32_e32 v60, 16, v36
	s_waitcnt lgkmcnt(5)
	v_lshlrev_b32_e32 v57, 16, v39
	s_waitcnt lgkmcnt(4)
	v_lshlrev_b32_e32 v54, 16, v40
	s_waitcnt lgkmcnt(3)
	v_lshlrev_b32_e32 v51, 16, v42
	s_waitcnt lgkmcnt(2)
	v_lshlrev_b32_e32 v48, 16, v43
	s_waitcnt lgkmcnt(1)
	v_lshlrev_b32_e32 v45, 16, v44
	s_waitcnt lgkmcnt(0)
	v_lshlrev_b32_e32 v42, 16, v46
	ds_read_u16 v35, v34 offset:40960
	ds_read_u16 v36, v34 offset:41984
	ds_read_u16 v39, v34 offset:43008
	ds_read_u16 v40, v34 offset:44032
	ds_read_u16 v43, v34 offset:45056
	ds_read_u16 v44, v34 offset:46080
	ds_read_u16 v46, v34 offset:47104
	ds_read_u16 v47, v34 offset:48128
	s_waitcnt lgkmcnt(7)
	v_lshlrev_b32_e32 v64, 16, v35
	s_waitcnt lgkmcnt(6)
	v_lshlrev_b32_e32 v61, 16, v36
	s_waitcnt lgkmcnt(5)
	v_lshlrev_b32_e32 v58, 16, v39
	s_waitcnt lgkmcnt(4)
	v_lshlrev_b32_e32 v55, 16, v40
	s_waitcnt lgkmcnt(3)
	v_lshlrev_b32_e32 v52, 16, v43
	s_waitcnt lgkmcnt(2)
	v_lshlrev_b32_e32 v49, 16, v44
	s_waitcnt lgkmcnt(0)
	v_lshlrev_b32_e32 v43, 16, v47
	ds_read_u16 v35, v34 offset:49152
	ds_read_u16 v36, v34 offset:50176
	ds_read_u16 v39, v34 offset:51200
	ds_read_u16 v40, v34 offset:52224
	ds_read_u16 v44, v34 offset:53248
	ds_read_u16 v47, v34 offset:54272
	ds_read_u16 v101, v34 offset:55296
	ds_read_u16 v34, v34 offset:56320
	s_waitcnt lgkmcnt(4)
	v_lshlrev_b32_e32 v56, 16, v40
	v_lshlrev_b32_e32 v40, 16, v37
	v_lshlrev_b32_e32 v37, 16, v91
	v_lshlrev_b32_e32 v59, 16, v39
	v_lshlrev_b32_e32 v39, 16, v38
	v_lshlrev_b32_e32 v38, 16, v90
	v_lshl_add_u32 v90, v29, 2, 0
	v_lshlrev_b32_e32 v62, 16, v36
	v_add_u32_e32 v36, 0xf800, v90
	v_lshlrev_b32_e32 v46, 16, v46
	v_lshlrev_b32_e32 v65, 16, v35
	s_waitcnt lgkmcnt(3)
	v_lshlrev_b32_e32 v53, 16, v44
	s_waitcnt lgkmcnt(2)
	v_lshlrev_b32_e32 v50, 16, v47
	s_waitcnt lgkmcnt(1)
	v_lshlrev_b32_e32 v47, 16, v101
	s_waitcnt lgkmcnt(0)
	v_lshlrev_b32_e32 v44, 16, v34
	v_lshlrev_b32_e32 v35, 16, v92
	s_movk_i32 s0, 0x1000
	v_lshlrev_b32_e32 v34, 16, v93
	s_mov_b64 s[10:11], 0x1000
	s_mov_b32 s12, 0x3b000000
	s_waitcnt vmcnt(0)
; __device__ __forceinline__ void conv_item(const Params& p, int l, int item) {
;     ...
; #pragma unroll
;         for (int t = 0; t < 32; ++t) {
;             float a = bias;
; #pragma unroll
;             for (int j = 0; j < 31; ++j) a = fmaf(wj[j], win[t + j], a);
;             CV[t * 512 + c] = a;
;         }
;     ...
;             bf16_t* gp = P1 + (long)(R0 + t) * P1W + 2048 + lane * 8;
;             uint4 gv = ld_nt_u4(gp);
	v_lshrrev_b32_e32 v156, 6, v208
	v_lshl_add_u32 v156, v156, 2, s3
	v_lshlrev_b32_e32 v156, 13, v156
	v_and_b32_e32 v157, 63, v208
	v_lshl_add_u32 v156, v157, 4, v156
	v_add_u32_e32 v156, 0x1000, v156
	global_load_dwordx4 v[140:143], v156, s[78:79] nt
	v_add_u32_e32 v156, 0x2000, v156
	global_load_dwordx4 v[144:147], v156, s[78:79] nt
	v_add_u32_e32 v156, 0x2000, v156
	global_load_dwordx4 v[148:151], v156, s[78:79] nt
	v_add_u32_e32 v156, 0x2000, v156
	global_load_dwordx4 v[152:155], v156, s[78:79] nt
	v_fma_f32 v91, v7, v94, v32
	v_fmac_f32_e32 v91, v6, v95
	v_fmac_f32_e32 v91, v5, v96
	v_fmac_f32_e32 v91, v4, v97
	v_fmac_f32_e32 v91, v3, v98
	v_fmac_f32_e32 v91, v2, v99
	v_fmac_f32_e32 v91, v1, v100
	v_fmac_f32_e32 v91, v0, v89
	v_fmac_f32_e32 v91, v15, v88
	v_fmac_f32_e32 v91, v14, v87
	v_fmac_f32_e32 v91, v13, v86
	v_fmac_f32_e32 v91, v12, v85
	v_fmac_f32_e32 v91, v11, v84
	v_fmac_f32_e32 v91, v10, v83
	v_fmac_f32_e32 v91, v9, v82
	v_fmac_f32_e32 v91, v8, v81
	v_fmac_f32_e32 v91, v23, v80
	v_fmac_f32_e32 v91, v22, v79
	v_fmac_f32_e32 v91, v21, v78
	v_fmac_f32_e32 v91, v20, v77
	v_fmac_f32_e32 v91, v19, v76
	v_fmac_f32_e32 v91, v18, v75
	v_fmac_f32_e32 v91, v17, v74
	v_fmac_f32_e32 v91, v16, v73
	v_fmac_f32_e32 v91, v33, v72
	v_fmac_f32_e32 v91, v31, v71
	v_fmac_f32_e32 v91, v30, v70
	v_fmac_f32_e32 v91, v27, v69
	v_fmac_f32_e32 v91, v26, v68
	v_fmac_f32_e32 v91, v25, v67
	v_fmac_f32_e32 v91, v24, v66
	ds_write_b32 v90, v91 offset:63488
	v_fma_f32 v90, v7, v95, v32
	v_fma_f32 v91, v7, v96, v32
	v_fmac_f32_e32 v90, v6, v96
	v_fmac_f32_e32 v91, v6, v97
	v_fmac_f32_e32 v90, v5, v97
	v_fmac_f32_e32 v91, v5, v98
	v_fmac_f32_e32 v90, v4, v98
	v_fmac_f32_e32 v91, v4, v99
	v_fmac_f32_e32 v90, v3, v99
	v_fmac_f32_e32 v91, v3, v100
	v_fmac_f32_e32 v90, v2, v100
	v_fmac_f32_e32 v91, v2, v89
	v_fmac_f32_e32 v90, v1, v89
	v_fmac_f32_e32 v91, v1, v88
	v_fmac_f32_e32 v90, v0, v88
	v_fmac_f32_e32 v91, v0, v87
	v_fmac_f32_e32 v90, v15, v87
	v_fmac_f32_e32 v91, v15, v86
	v_fmac_f32_e32 v90, v14, v86
	v_fmac_f32_e32 v91, v14, v85
	v_fmac_f32_e32 v90, v13, v85
	v_fmac_f32_e32 v91, v13, v84
	v_fmac_f32_e32 v90, v12, v84
	v_fmac_f32_e32 v91, v12, v83
	v_fmac_f32_e32 v90, v11, v83
	v_fmac_f32_e32 v91, v11, v82
	v_fmac_f32_e32 v90, v10, v82
	v_fmac_f32_e32 v91, v10, v81
	v_fmac_f32_e32 v90, v9, v81
	v_fmac_f32_e32 v91, v9, v80
	v_fmac_f32_e32 v90, v8, v80
	v_fmac_f32_e32 v91, v8, v79
	v_fmac_f32_e32 v90, v23, v79
	v_fmac_f32_e32 v91, v23, v78
	v_fmac_f32_e32 v90, v22, v78
	v_fmac_f32_e32 v91, v22, v77
	v_fmac_f32_e32 v90, v21, v77
	v_fmac_f32_e32 v91, v21, v76
	v_fmac_f32_e32 v90, v20, v76
	v_fmac_f32_e32 v91, v20, v75
	v_fmac_f32_e32 v90, v19, v75
	v_fmac_f32_e32 v91, v19, v74
	v_fmac_f32_e32 v90, v18, v74
	v_fmac_f32_e32 v91, v18, v73
	v_fmac_f32_e32 v90, v17, v73
	v_fmac_f32_e32 v91, v17, v72
	v_fmac_f32_e32 v90, v16, v72
	v_fmac_f32_e32 v91, v16, v71
	v_fmac_f32_e32 v90, v33, v71
	v_fmac_f32_e32 v91, v33, v70
	v_fmac_f32_e32 v90, v31, v70
	v_fmac_f32_e32 v91, v31, v69
	v_fmac_f32_e32 v90, v30, v69
	v_fmac_f32_e32 v91, v30, v68
	v_fmac_f32_e32 v90, v27, v68
	v_fmac_f32_e32 v91, v27, v67
	v_fmac_f32_e32 v90, v26, v67
	v_fmac_f32_e32 v91, v26, v66
	v_fmac_f32_e32 v90, v25, v66
	v_fmac_f32_e32 v91, v25, v41
	v_fmac_f32_e32 v90, v24, v41
	v_fmac_f32_e32 v91, v24, v63
	ds_write2st64_b32 v36, v90, v91 offset0:8 offset1:16
	v_fma_f32 v90, v7, v97, v32
	v_fma_f32 v91, v7, v98, v32
	v_fmac_f32_e32 v90, v6, v98
	v_fmac_f32_e32 v91, v6, v99
	v_fmac_f32_e32 v90, v5, v99
	v_fmac_f32_e32 v91, v5, v100
	v_fmac_f32_e32 v90, v4, v100
	v_fmac_f32_e32 v91, v4, v89
	v_fmac_f32_e32 v90, v3, v89
	v_fmac_f32_e32 v91, v3, v88
	v_fmac_f32_e32 v90, v2, v88
	v_fmac_f32_e32 v91, v2, v87
	v_fmac_f32_e32 v90, v1, v87
	v_fmac_f32_e32 v91, v1, v86
	v_fmac_f32_e32 v90, v0, v86
	v_fmac_f32_e32 v91, v0, v85
	v_fmac_f32_e32 v90, v15, v85
	v_fmac_f32_e32 v91, v15, v84
	v_fmac_f32_e32 v90, v14, v84
	v_fmac_f32_e32 v91, v14, v83
	v_fmac_f32_e32 v90, v13, v83
	v_fmac_f32_e32 v91, v13, v82
	v_fmac_f32_e32 v90, v12, v82
	v_fmac_f32_e32 v91, v12, v81
	v_fmac_f32_e32 v90, v11, v81
	v_fmac_f32_e32 v91, v11, v80
	v_fmac_f32_e32 v90, v10, v80
	v_fmac_f32_e32 v91, v10, v79
	v_fmac_f32_e32 v90, v9, v79
	v_fmac_f32_e32 v91, v9, v78
	v_fmac_f32_e32 v90, v8, v78
	v_fmac_f32_e32 v91, v8, v77
	v_fmac_f32_e32 v90, v23, v77
	v_fmac_f32_e32 v91, v23, v76
	v_fmac_f32_e32 v90, v22, v76
	v_fmac_f32_e32 v91, v22, v75
	v_fmac_f32_e32 v90, v21, v75
	v_fmac_f32_e32 v91, v21, v74
	v_fmac_f32_e32 v90, v20, v74
	v_fmac_f32_e32 v91, v20, v73
	v_fmac_f32_e32 v90, v19, v73
	v_fmac_f32_e32 v91, v19, v72
	v_fmac_f32_e32 v90, v18, v72
	v_fmac_f32_e32 v91, v18, v71
	v_fmac_f32_e32 v90, v17, v71
	v_fmac_f32_e32 v91, v17, v70
	v_fmac_f32_e32 v90, v16, v70
	v_fmac_f32_e32 v91, v16, v69
	v_fmac_f32_e32 v90, v33, v69
	v_fmac_f32_e32 v91, v33, v68
	v_fmac_f32_e32 v90, v31, v68
	v_fmac_f32_e32 v91, v31, v67
	v_fmac_f32_e32 v90, v30, v67
	v_fmac_f32_e32 v91, v30, v66
	v_fmac_f32_e32 v90, v27, v66
	v_fmac_f32_e32 v91, v27, v41
	v_fmac_f32_e32 v90, v26, v41
	v_fmac_f32_e32 v91, v26, v63
	v_fmac_f32_e32 v90, v25, v63
	v_fmac_f32_e32 v91, v25, v60
	v_fmac_f32_e32 v90, v24, v60
	v_fmac_f32_e32 v91, v24, v57
	ds_write2st64_b32 v36, v90, v91 offset0:24 offset1:32
	v_fma_f32 v90, v7, v99, v32
	v_fmac_f32_e32 v90, v6, v100
	v_fma_f32 v91, v7, v100, v32
	v_fmac_f32_e32 v90, v5, v89
	v_fmac_f32_e32 v91, v6, v89
	v_fma_f32 v89, v7, v89, v32
	v_fmac_f32_e32 v90, v4, v88
	v_fmac_f32_e32 v91, v5, v88
	v_fmac_f32_e32 v89, v6, v88
	v_fma_f32 v88, v7, v88, v32
	v_fmac_f32_e32 v90, v3, v87
	v_fmac_f32_e32 v91, v4, v87
	v_fmac_f32_e32 v89, v5, v87
; __device__ __forceinline__ void conv_item(const Params& p, int l, int item) {
;     ...
; #pragma unroll
;         for (int t = 0; t < 32; ++t) {
;             float a = bias;
; #pragma unroll
;             for (int j = 0; j < 31; ++j) a = fmaf(wj[j], win[t + j], a);
;             CV[t * 512 + c] = a;
;         }
	v_fmac_f32_e32 v88, v6, v87
	v_fma_f32 v87, v7, v87, v32
	v_fmac_f32_e32 v90, v2, v86
	v_fmac_f32_e32 v91, v3, v86
	v_fmac_f32_e32 v89, v4, v86
	v_fmac_f32_e32 v88, v5, v86
	v_fmac_f32_e32 v87, v6, v86
	v_fma_f32 v86, v7, v86, v32
	v_fmac_f32_e32 v90, v1, v85
	v_fmac_f32_e32 v91, v2, v85
	v_fmac_f32_e32 v89, v3, v85
	v_fmac_f32_e32 v88, v4, v85
	v_fmac_f32_e32 v87, v5, v85
	v_fmac_f32_e32 v86, v6, v85
	v_fma_f32 v85, v7, v85, v32
	v_fmac_f32_e32 v90, v0, v84
	v_fmac_f32_e32 v91, v1, v84
	v_fmac_f32_e32 v89, v2, v84
	v_fmac_f32_e32 v88, v3, v84
	v_fmac_f32_e32 v87, v4, v84
	v_fmac_f32_e32 v86, v5, v84
	v_fmac_f32_e32 v85, v6, v84
	v_fma_f32 v84, v7, v84, v32
	v_fmac_f32_e32 v90, v15, v83
	v_fmac_f32_e32 v91, v0, v83
	v_fmac_f32_e32 v89, v1, v83
	v_fmac_f32_e32 v88, v2, v83
	v_fmac_f32_e32 v87, v3, v83
	v_fmac_f32_e32 v86, v4, v83
	v_fmac_f32_e32 v85, v5, v83
	v_fmac_f32_e32 v84, v6, v83
	v_fma_f32 v83, v7, v83, v32
	v_fmac_f32_e32 v90, v14, v82
	v_fmac_f32_e32 v91, v15, v82
	v_fmac_f32_e32 v89, v0, v82
	v_fmac_f32_e32 v88, v1, v82
	v_fmac_f32_e32 v87, v2, v82
	v_fmac_f32_e32 v86, v3, v82
	v_fmac_f32_e32 v85, v4, v82
	v_fmac_f32_e32 v84, v5, v82
	v_fmac_f32_e32 v83, v6, v82
	v_fma_f32 v82, v7, v82, v32
	v_fmac_f32_e32 v90, v13, v81
	v_fmac_f32_e32 v91, v14, v81
	v_fmac_f32_e32 v89, v15, v81
	v_fmac_f32_e32 v88, v0, v81
	v_fmac_f32_e32 v87, v1, v81
	v_fmac_f32_e32 v86, v2, v81
	v_fmac_f32_e32 v85, v3, v81
	v_fmac_f32_e32 v84, v4, v81
	v_fmac_f32_e32 v83, v5, v81
	v_fmac_f32_e32 v82, v6, v81
	v_fma_f32 v81, v7, v81, v32
	v_fmac_f32_e32 v90, v12, v80
	v_fmac_f32_e32 v91, v13, v80
	v_fmac_f32_e32 v89, v14, v80
	v_fmac_f32_e32 v88, v15, v80
	v_fmac_f32_e32 v87, v0, v80
	v_fmac_f32_e32 v86, v1, v80
	v_fmac_f32_e32 v85, v2, v80
	v_fmac_f32_e32 v84, v3, v80
	v_fmac_f32_e32 v83, v4, v80
	v_fmac_f32_e32 v82, v5, v80
	v_fmac_f32_e32 v81, v6, v80
	v_fma_f32 v80, v7, v80, v32
	v_fmac_f32_e32 v90, v11, v79
	v_fmac_f32_e32 v91, v12, v79
	v_fmac_f32_e32 v89, v13, v79
	v_fmac_f32_e32 v88, v14, v79
	v_fmac_f32_e32 v87, v15, v79
	v_fmac_f32_e32 v86, v0, v79
	v_fmac_f32_e32 v85, v1, v79
	v_fmac_f32_e32 v84, v2, v79
	v_fmac_f32_e32 v83, v3, v79
	v_fmac_f32_e32 v82, v4, v79
	v_fmac_f32_e32 v81, v5, v79
	v_fmac_f32_e32 v80, v6, v79
	v_fma_f32 v79, v7, v79, v32
	v_fmac_f32_e32 v90, v10, v78
	v_fmac_f32_e32 v91, v11, v78
	v_fmac_f32_e32 v89, v12, v78
	v_fmac_f32_e32 v88, v13, v78
	v_fmac_f32_e32 v87, v14, v78
	v_fmac_f32_e32 v86, v15, v78
	v_fmac_f32_e32 v85, v0, v78
	v_fmac_f32_e32 v84, v1, v78
	v_fmac_f32_e32 v83, v2, v78
	v_fmac_f32_e32 v82, v3, v78
	v_fmac_f32_e32 v81, v4, v78
	v_fmac_f32_e32 v80, v5, v78
	v_fmac_f32_e32 v79, v6, v78
	v_fma_f32 v78, v7, v78, v32
	v_fmac_f32_e32 v90, v9, v77
	v_fmac_f32_e32 v91, v10, v77
	v_fmac_f32_e32 v89, v11, v77
	v_fmac_f32_e32 v88, v12, v77
	v_fmac_f32_e32 v87, v13, v77
	v_fmac_f32_e32 v86, v14, v77
	v_fmac_f32_e32 v85, v15, v77
	v_fmac_f32_e32 v84, v0, v77
	v_fmac_f32_e32 v83, v1, v77
	v_fmac_f32_e32 v82, v2, v77
	v_fmac_f32_e32 v81, v3, v77
	v_fmac_f32_e32 v80, v4, v77
	v_fmac_f32_e32 v79, v5, v77
	v_fmac_f32_e32 v78, v6, v77
	v_fma_f32 v77, v7, v77, v32
	v_fmac_f32_e32 v90, v8, v76
	v_fmac_f32_e32 v91, v9, v76
	v_fmac_f32_e32 v89, v10, v76
	v_fmac_f32_e32 v88, v11, v76
	v_fmac_f32_e32 v87, v12, v76
	v_fmac_f32_e32 v86, v13, v76
	v_fmac_f32_e32 v85, v14, v76
	v_fmac_f32_e32 v84, v15, v76
	v_fmac_f32_e32 v83, v0, v76
	v_fmac_f32_e32 v82, v1, v76
	v_fmac_f32_e32 v81, v2, v76
	v_fmac_f32_e32 v80, v3, v76
	v_fmac_f32_e32 v79, v4, v76
	v_fmac_f32_e32 v78, v5, v76
	v_fmac_f32_e32 v77, v6, v76
	v_fma_f32 v76, v7, v76, v32
	v_fmac_f32_e32 v90, v23, v75
	v_fmac_f32_e32 v91, v8, v75
	v_fmac_f32_e32 v89, v9, v75
	v_fmac_f32_e32 v88, v10, v75
	v_fmac_f32_e32 v87, v11, v75
	v_fmac_f32_e32 v86, v12, v75
	v_fmac_f32_e32 v85, v13, v75
	v_fmac_f32_e32 v84, v14, v75
	v_fmac_f32_e32 v83, v15, v75
	v_fmac_f32_e32 v82, v0, v75
	v_fmac_f32_e32 v81, v1, v75
	v_fmac_f32_e32 v80, v2, v75
	v_fmac_f32_e32 v79, v3, v75
	v_fmac_f32_e32 v78, v4, v75
	v_fmac_f32_e32 v77, v5, v75
	v_fmac_f32_e32 v76, v6, v75
	v_fma_f32 v75, v7, v75, v32
	v_fmac_f32_e32 v90, v22, v74
	v_fmac_f32_e32 v91, v23, v74
	v_fmac_f32_e32 v89, v8, v74
	v_fmac_f32_e32 v88, v9, v74
	v_fmac_f32_e32 v87, v10, v74
	v_fmac_f32_e32 v86, v11, v74
	v_fmac_f32_e32 v85, v12, v74
	v_fmac_f32_e32 v84, v13, v74
	v_fmac_f32_e32 v83, v14, v74
	v_fmac_f32_e32 v82, v15, v74
	v_fmac_f32_e32 v81, v0, v74
	v_fmac_f32_e32 v80, v1, v74
	v_fmac_f32_e32 v79, v2, v74
	v_fmac_f32_e32 v78, v3, v74
	v_fmac_f32_e32 v77, v4, v74
	v_fmac_f32_e32 v76, v5, v74
	v_fmac_f32_e32 v75, v6, v74
	v_fma_f32 v74, v7, v74, v32
	v_fmac_f32_e32 v90, v21, v73
	v_fmac_f32_e32 v91, v22, v73
	v_fmac_f32_e32 v89, v23, v73
	v_fmac_f32_e32 v88, v8, v73
	v_fmac_f32_e32 v87, v9, v73
	v_fmac_f32_e32 v86, v10, v73
	v_fmac_f32_e32 v85, v11, v73
	v_fmac_f32_e32 v84, v12, v73
	v_fmac_f32_e32 v83, v13, v73
	v_fmac_f32_e32 v82, v14, v73
	v_fmac_f32_e32 v81, v15, v73
	v_fmac_f32_e32 v80, v0, v73
	v_fmac_f32_e32 v79, v1, v73
	v_fmac_f32_e32 v78, v2, v73
	v_fmac_f32_e32 v77, v3, v73
	v_fmac_f32_e32 v76, v4, v73
	v_fmac_f32_e32 v75, v5, v73
	v_fmac_f32_e32 v74, v6, v73
	v_fma_f32 v73, v7, v73, v32
	v_fmac_f32_e32 v90, v20, v72
	v_fmac_f32_e32 v91, v21, v72
	v_fmac_f32_e32 v89, v22, v72
	v_fmac_f32_e32 v88, v23, v72
	v_fmac_f32_e32 v87, v8, v72
	v_fmac_f32_e32 v86, v9, v72
	v_fmac_f32_e32 v85, v10, v72
	v_fmac_f32_e32 v84, v11, v72
	v_fmac_f32_e32 v83, v12, v72
	v_fmac_f32_e32 v82, v13, v72
	v_fmac_f32_e32 v81, v14, v72
	v_fmac_f32_e32 v80, v15, v72
	v_fmac_f32_e32 v79, v0, v72
	v_fmac_f32_e32 v78, v1, v72
	v_fmac_f32_e32 v77, v2, v72
; __device__ __forceinline__ void conv_item(const Params& p, int l, int item) {
;     ...
; #pragma unroll
;         for (int t = 0; t < 32; ++t) {
;             float a = bias;
; #pragma unroll
;             for (int j = 0; j < 31; ++j) a = fmaf(wj[j], win[t + j], a);
;             CV[t * 512 + c] = a;
;         }
	v_fmac_f32_e32 v76, v3, v72
	v_fmac_f32_e32 v75, v4, v72
	v_fmac_f32_e32 v74, v5, v72
	v_fmac_f32_e32 v73, v6, v72
	v_fma_f32 v72, v7, v72, v32
	v_fmac_f32_e32 v90, v19, v71
	v_fmac_f32_e32 v91, v20, v71
	v_fmac_f32_e32 v89, v21, v71
	v_fmac_f32_e32 v88, v22, v71
	v_fmac_f32_e32 v87, v23, v71
	v_fmac_f32_e32 v86, v8, v71
	v_fmac_f32_e32 v85, v9, v71
	v_fmac_f32_e32 v84, v10, v71
	v_fmac_f32_e32 v83, v11, v71
	v_fmac_f32_e32 v82, v12, v71
	v_fmac_f32_e32 v81, v13, v71
	v_fmac_f32_e32 v80, v14, v71
	v_fmac_f32_e32 v79, v15, v71
	v_fmac_f32_e32 v78, v0, v71
	v_fmac_f32_e32 v77, v1, v71
	v_fmac_f32_e32 v76, v2, v71
	v_fmac_f32_e32 v75, v3, v71
	v_fmac_f32_e32 v74, v4, v71
	v_fmac_f32_e32 v73, v5, v71
	v_fmac_f32_e32 v72, v6, v71
	v_fma_f32 v71, v7, v71, v32
	v_fmac_f32_e32 v90, v18, v70
	v_fmac_f32_e32 v91, v19, v70
	v_fmac_f32_e32 v89, v20, v70
	v_fmac_f32_e32 v88, v21, v70
	v_fmac_f32_e32 v87, v22, v70
	v_fmac_f32_e32 v86, v23, v70
	v_fmac_f32_e32 v85, v8, v70
	v_fmac_f32_e32 v84, v9, v70
	v_fmac_f32_e32 v83, v10, v70
	v_fmac_f32_e32 v82, v11, v70
	v_fmac_f32_e32 v81, v12, v70
	v_fmac_f32_e32 v80, v13, v70
	v_fmac_f32_e32 v79, v14, v70
	v_fmac_f32_e32 v78, v15, v70
	v_fmac_f32_e32 v77, v0, v70
	v_fmac_f32_e32 v76, v1, v70
	v_fmac_f32_e32 v75, v2, v70
	v_fmac_f32_e32 v74, v3, v70
	v_fmac_f32_e32 v73, v4, v70
	v_fmac_f32_e32 v72, v5, v70
	v_fmac_f32_e32 v71, v6, v70
	v_fma_f32 v70, v7, v70, v32
	v_fmac_f32_e32 v90, v17, v69
	v_fmac_f32_e32 v91, v18, v69
	v_fmac_f32_e32 v89, v19, v69
	v_fmac_f32_e32 v88, v20, v69
	v_fmac_f32_e32 v87, v21, v69
	v_fmac_f32_e32 v86, v22, v69
	v_fmac_f32_e32 v85, v23, v69
	v_fmac_f32_e32 v84, v8, v69
	v_fmac_f32_e32 v83, v9, v69
	v_fmac_f32_e32 v82, v10, v69
	v_fmac_f32_e32 v81, v11, v69
	v_fmac_f32_e32 v80, v12, v69
	v_fmac_f32_e32 v79, v13, v69
	v_fmac_f32_e32 v78, v14, v69
	v_fmac_f32_e32 v77, v15, v69
	v_fmac_f32_e32 v76, v0, v69
	v_fmac_f32_e32 v75, v1, v69
	v_fmac_f32_e32 v74, v2, v69
	v_fmac_f32_e32 v73, v3, v69
	v_fmac_f32_e32 v72, v4, v69
	v_fmac_f32_e32 v71, v5, v69
	v_fmac_f32_e32 v70, v6, v69
	v_fma_f32 v69, v7, v69, v32
	v_fmac_f32_e32 v90, v16, v68
	v_fmac_f32_e32 v91, v17, v68
	v_fmac_f32_e32 v89, v18, v68
	v_fmac_f32_e32 v88, v19, v68
	v_fmac_f32_e32 v87, v20, v68
	v_fmac_f32_e32 v86, v21, v68
	v_fmac_f32_e32 v85, v22, v68
	v_fmac_f32_e32 v84, v23, v68
	v_fmac_f32_e32 v83, v8, v68
	v_fmac_f32_e32 v82, v9, v68
	v_fmac_f32_e32 v81, v10, v68
	v_fmac_f32_e32 v80, v11, v68
	v_fmac_f32_e32 v79, v12, v68
	v_fmac_f32_e32 v78, v13, v68
	v_fmac_f32_e32 v77, v14, v68
	v_fmac_f32_e32 v76, v15, v68
	v_fmac_f32_e32 v75, v0, v68
	v_fmac_f32_e32 v74, v1, v68
	v_fmac_f32_e32 v73, v2, v68
	v_fmac_f32_e32 v72, v3, v68
	v_fmac_f32_e32 v71, v4, v68
	v_fmac_f32_e32 v70, v5, v68
	v_fmac_f32_e32 v69, v6, v68
	v_fma_f32 v68, v7, v68, v32
	v_fmac_f32_e32 v90, v33, v67
	v_fmac_f32_e32 v91, v16, v67
	v_fmac_f32_e32 v89, v17, v67
	v_fmac_f32_e32 v88, v18, v67
	v_fmac_f32_e32 v87, v19, v67
	v_fmac_f32_e32 v86, v20, v67
	v_fmac_f32_e32 v85, v21, v67
	v_fmac_f32_e32 v84, v22, v67
	v_fmac_f32_e32 v83, v23, v67
	v_fmac_f32_e32 v82, v8, v67
	v_fmac_f32_e32 v81, v9, v67
	v_fmac_f32_e32 v80, v10, v67
	v_fmac_f32_e32 v79, v11, v67
	v_fmac_f32_e32 v78, v12, v67
	v_fmac_f32_e32 v77, v13, v67
	v_fmac_f32_e32 v76, v14, v67
	v_fmac_f32_e32 v75, v15, v67
	v_fmac_f32_e32 v74, v0, v67
	v_fmac_f32_e32 v73, v1, v67
	v_fmac_f32_e32 v72, v2, v67
	v_fmac_f32_e32 v71, v3, v67
	v_fmac_f32_e32 v70, v4, v67
	v_fmac_f32_e32 v69, v5, v67
	v_fmac_f32_e32 v68, v6, v67
	v_fma_f32 v67, v7, v67, v32
	v_fmac_f32_e32 v90, v31, v66
	v_fmac_f32_e32 v91, v33, v66
	v_fmac_f32_e32 v89, v16, v66
	v_fmac_f32_e32 v88, v17, v66
	v_fmac_f32_e32 v87, v18, v66
	v_fmac_f32_e32 v86, v19, v66
	v_fmac_f32_e32 v85, v20, v66
	v_fmac_f32_e32 v84, v21, v66
	v_fmac_f32_e32 v83, v22, v66
	v_fmac_f32_e32 v82, v23, v66
	v_fmac_f32_e32 v81, v8, v66
	v_fmac_f32_e32 v80, v9, v66
	v_fmac_f32_e32 v79, v10, v66
	v_fmac_f32_e32 v78, v11, v66
	v_fmac_f32_e32 v77, v12, v66
	v_fmac_f32_e32 v76, v13, v66
	v_fmac_f32_e32 v75, v14, v66
	v_fmac_f32_e32 v74, v15, v66
	v_fmac_f32_e32 v73, v0, v66
	v_fmac_f32_e32 v72, v1, v66
	v_fmac_f32_e32 v71, v2, v66
	v_fmac_f32_e32 v70, v3, v66
	v_fmac_f32_e32 v69, v4, v66
	v_fmac_f32_e32 v68, v5, v66
	v_fmac_f32_e32 v67, v6, v66
	v_fma_f32 v66, v7, v66, v32
	v_fmac_f32_e32 v32, v7, v41
	v_fmac_f32_e32 v66, v6, v41
	v_fmac_f32_e32 v32, v6, v63
	v_fmac_f32_e32 v67, v5, v41
	v_fmac_f32_e32 v66, v5, v63
	v_fmac_f32_e32 v32, v5, v60
	v_fmac_f32_e32 v68, v4, v41
	v_fmac_f32_e32 v67, v4, v63
	v_fmac_f32_e32 v66, v4, v60
	v_fmac_f32_e32 v32, v4, v57
	v_fmac_f32_e32 v69, v3, v41
	v_fmac_f32_e32 v68, v3, v63
	v_fmac_f32_e32 v67, v3, v60
	v_fmac_f32_e32 v66, v3, v57
	v_fmac_f32_e32 v32, v3, v54
	v_fmac_f32_e32 v70, v2, v41
	v_fmac_f32_e32 v69, v2, v63
	v_fmac_f32_e32 v68, v2, v60
	v_fmac_f32_e32 v67, v2, v57
	v_fmac_f32_e32 v66, v2, v54
	v_fmac_f32_e32 v32, v2, v51
	v_fmac_f32_e32 v71, v1, v41
	v_fmac_f32_e32 v70, v1, v63
	v_fmac_f32_e32 v69, v1, v60
	v_fmac_f32_e32 v68, v1, v57
	v_fmac_f32_e32 v67, v1, v54
	v_fmac_f32_e32 v66, v1, v51
	v_fmac_f32_e32 v32, v1, v48
	v_fmac_f32_e32 v72, v0, v41
	v_fmac_f32_e32 v71, v0, v63
	v_fmac_f32_e32 v70, v0, v60
	v_fmac_f32_e32 v69, v0, v57
	v_fmac_f32_e32 v68, v0, v54
	v_fmac_f32_e32 v67, v0, v51
	v_fmac_f32_e32 v66, v0, v48
	v_fmac_f32_e32 v32, v0, v45
	v_fmac_f32_e32 v73, v15, v41
	v_fmac_f32_e32 v72, v15, v63
	v_fmac_f32_e32 v71, v15, v60
	v_fmac_f32_e32 v70, v15, v57
	v_fmac_f32_e32 v69, v15, v54
	v_fmac_f32_e32 v68, v15, v51
	v_fmac_f32_e32 v67, v15, v48
	v_fmac_f32_e32 v66, v15, v45
	v_fmac_f32_e32 v32, v15, v42
; __device__ __forceinline__ void conv_item(const Params& p, int l, int item) {
;     ...
; #pragma unroll
;         for (int t = 0; t < 32; ++t) {
;             float a = bias;
; #pragma unroll
;             for (int j = 0; j < 31; ++j) a = fmaf(wj[j], win[t + j], a);
;             CV[t * 512 + c] = a;
;         }
	v_fmac_f32_e32 v74, v14, v41
	v_fmac_f32_e32 v73, v14, v63
	v_fmac_f32_e32 v72, v14, v60
	v_fmac_f32_e32 v71, v14, v57
	v_fmac_f32_e32 v70, v14, v54
	v_fmac_f32_e32 v69, v14, v51
	v_fmac_f32_e32 v68, v14, v48
	v_fmac_f32_e32 v67, v14, v45
	v_fmac_f32_e32 v66, v14, v42
	v_fmac_f32_e32 v32, v14, v64
	v_fmac_f32_e32 v75, v13, v41
	v_fmac_f32_e32 v74, v13, v63
	v_fmac_f32_e32 v73, v13, v60
	v_fmac_f32_e32 v72, v13, v57
	v_fmac_f32_e32 v71, v13, v54
	v_fmac_f32_e32 v70, v13, v51
	v_fmac_f32_e32 v69, v13, v48
	v_fmac_f32_e32 v68, v13, v45
	v_fmac_f32_e32 v67, v13, v42
	v_fmac_f32_e32 v66, v13, v64
	v_fmac_f32_e32 v32, v13, v61
	v_fmac_f32_e32 v76, v12, v41
	v_fmac_f32_e32 v75, v12, v63
	v_fmac_f32_e32 v74, v12, v60
	v_fmac_f32_e32 v73, v12, v57
	v_fmac_f32_e32 v72, v12, v54
	v_fmac_f32_e32 v71, v12, v51
	v_fmac_f32_e32 v70, v12, v48
	v_fmac_f32_e32 v69, v12, v45
	v_fmac_f32_e32 v68, v12, v42
	v_fmac_f32_e32 v67, v12, v64
	v_fmac_f32_e32 v66, v12, v61
	v_fmac_f32_e32 v32, v12, v58
	v_fmac_f32_e32 v77, v11, v41
	v_fmac_f32_e32 v76, v11, v63
	v_fmac_f32_e32 v75, v11, v60
	v_fmac_f32_e32 v74, v11, v57
	v_fmac_f32_e32 v73, v11, v54
	v_fmac_f32_e32 v72, v11, v51
	v_fmac_f32_e32 v71, v11, v48
	v_fmac_f32_e32 v70, v11, v45
	v_fmac_f32_e32 v69, v11, v42
	v_fmac_f32_e32 v68, v11, v64
	v_fmac_f32_e32 v67, v11, v61
	v_fmac_f32_e32 v66, v11, v58
	v_fmac_f32_e32 v32, v11, v55
	v_fmac_f32_e32 v78, v10, v41
	v_fmac_f32_e32 v77, v10, v63
	v_fmac_f32_e32 v76, v10, v60
	v_fmac_f32_e32 v75, v10, v57
	v_fmac_f32_e32 v74, v10, v54
	v_fmac_f32_e32 v73, v10, v51
	v_fmac_f32_e32 v72, v10, v48
	v_fmac_f32_e32 v71, v10, v45
	v_fmac_f32_e32 v70, v10, v42
	v_fmac_f32_e32 v69, v10, v64
	v_fmac_f32_e32 v68, v10, v61
	v_fmac_f32_e32 v67, v10, v58
	v_fmac_f32_e32 v66, v10, v55
	v_fmac_f32_e32 v32, v10, v52
	v_fmac_f32_e32 v79, v9, v41
	v_fmac_f32_e32 v78, v9, v63
	v_fmac_f32_e32 v77, v9, v60
	v_fmac_f32_e32 v76, v9, v57
	v_fmac_f32_e32 v75, v9, v54
	v_fmac_f32_e32 v74, v9, v51
	v_fmac_f32_e32 v73, v9, v48
	v_fmac_f32_e32 v72, v9, v45
	v_fmac_f32_e32 v71, v9, v42
	v_fmac_f32_e32 v70, v9, v64
	v_fmac_f32_e32 v69, v9, v61
	v_fmac_f32_e32 v68, v9, v58
	v_fmac_f32_e32 v67, v9, v55
	v_fmac_f32_e32 v66, v9, v52
	v_fmac_f32_e32 v32, v9, v49
	v_fmac_f32_e32 v80, v8, v41
	v_fmac_f32_e32 v79, v8, v63
	v_fmac_f32_e32 v78, v8, v60
	v_fmac_f32_e32 v77, v8, v57
	v_fmac_f32_e32 v76, v8, v54
	v_fmac_f32_e32 v75, v8, v51
	v_fmac_f32_e32 v74, v8, v48
	v_fmac_f32_e32 v73, v8, v45
	v_fmac_f32_e32 v72, v8, v42
	v_fmac_f32_e32 v71, v8, v64
	v_fmac_f32_e32 v70, v8, v61
	v_fmac_f32_e32 v69, v8, v58
	v_fmac_f32_e32 v68, v8, v55
	v_fmac_f32_e32 v67, v8, v52
	v_fmac_f32_e32 v66, v8, v49
	v_fmac_f32_e32 v32, v8, v46
	v_fmac_f32_e32 v81, v23, v41
	v_fmac_f32_e32 v80, v23, v63
	v_fmac_f32_e32 v79, v23, v60
	v_fmac_f32_e32 v78, v23, v57
	v_fmac_f32_e32 v77, v23, v54
	v_fmac_f32_e32 v76, v23, v51
	v_fmac_f32_e32 v75, v23, v48
	v_fmac_f32_e32 v74, v23, v45
	v_fmac_f32_e32 v73, v23, v42
	v_fmac_f32_e32 v72, v23, v64
	v_fmac_f32_e32 v71, v23, v61
	v_fmac_f32_e32 v70, v23, v58
	v_fmac_f32_e32 v69, v23, v55
	v_fmac_f32_e32 v68, v23, v52
	v_fmac_f32_e32 v67, v23, v49
	v_fmac_f32_e32 v66, v23, v46
	v_fmac_f32_e32 v32, v23, v43
	v_fmac_f32_e32 v82, v22, v41
	v_fmac_f32_e32 v81, v22, v63
	v_fmac_f32_e32 v80, v22, v60
	v_fmac_f32_e32 v79, v22, v57
	v_fmac_f32_e32 v78, v22, v54
	v_fmac_f32_e32 v77, v22, v51
	v_fmac_f32_e32 v76, v22, v48
	v_fmac_f32_e32 v75, v22, v45
	v_fmac_f32_e32 v74, v22, v42
	v_fmac_f32_e32 v73, v22, v64
	v_fmac_f32_e32 v72, v22, v61
	v_fmac_f32_e32 v71, v22, v58
	v_fmac_f32_e32 v70, v22, v55
	v_fmac_f32_e32 v69, v22, v52
	v_fmac_f32_e32 v68, v22, v49
	v_fmac_f32_e32 v67, v22, v46
	v_fmac_f32_e32 v66, v22, v43
	v_fmac_f32_e32 v32, v22, v65
	v_fmac_f32_e32 v83, v21, v41
	v_fmac_f32_e32 v82, v21, v63
	v_fmac_f32_e32 v81, v21, v60
	v_fmac_f32_e32 v80, v21, v57
	v_fmac_f32_e32 v79, v21, v54
	v_fmac_f32_e32 v78, v21, v51
	v_fmac_f32_e32 v77, v21, v48
	v_fmac_f32_e32 v76, v21, v45
	v_fmac_f32_e32 v75, v21, v42
	v_fmac_f32_e32 v74, v21, v64
	v_fmac_f32_e32 v73, v21, v61
	v_fmac_f32_e32 v72, v21, v58
	v_fmac_f32_e32 v71, v21, v55
	v_fmac_f32_e32 v70, v21, v52
	v_fmac_f32_e32 v69, v21, v49
	v_fmac_f32_e32 v68, v21, v46
	v_fmac_f32_e32 v67, v21, v43
	v_fmac_f32_e32 v66, v21, v65
	v_fmac_f32_e32 v32, v21, v62
	v_fmac_f32_e32 v84, v20, v41
	v_fmac_f32_e32 v83, v20, v63
	v_fmac_f32_e32 v82, v20, v60
	v_fmac_f32_e32 v81, v20, v57
	v_fmac_f32_e32 v80, v20, v54
	v_fmac_f32_e32 v79, v20, v51
	v_fmac_f32_e32 v78, v20, v48
	v_fmac_f32_e32 v77, v20, v45
	v_fmac_f32_e32 v76, v20, v42
	v_fmac_f32_e32 v75, v20, v64
	v_fmac_f32_e32 v74, v20, v61
	v_fmac_f32_e32 v73, v20, v58
	v_fmac_f32_e32 v72, v20, v55
	v_fmac_f32_e32 v71, v20, v52
	v_fmac_f32_e32 v70, v20, v49
	v_fmac_f32_e32 v69, v20, v46
	v_fmac_f32_e32 v68, v20, v43
	v_fmac_f32_e32 v67, v20, v65
	v_fmac_f32_e32 v66, v20, v62
	v_fmac_f32_e32 v32, v20, v59
	v_fmac_f32_e32 v85, v19, v41
	v_fmac_f32_e32 v84, v19, v63
	v_fmac_f32_e32 v83, v19, v60
	v_fmac_f32_e32 v82, v19, v57
	v_fmac_f32_e32 v81, v19, v54
	v_fmac_f32_e32 v80, v19, v51
	v_fmac_f32_e32 v79, v19, v48
	v_fmac_f32_e32 v78, v19, v45
	v_fmac_f32_e32 v77, v19, v42
	v_fmac_f32_e32 v76, v19, v64
	v_fmac_f32_e32 v75, v19, v61
	v_fmac_f32_e32 v74, v19, v58
	v_fmac_f32_e32 v73, v19, v55
	v_fmac_f32_e32 v72, v19, v52
	v_fmac_f32_e32 v71, v19, v49
	v_fmac_f32_e32 v70, v19, v46
	v_fmac_f32_e32 v69, v19, v43
	v_fmac_f32_e32 v68, v19, v65
	v_fmac_f32_e32 v67, v19, v62
	v_fmac_f32_e32 v66, v19, v59
	v_fmac_f32_e32 v32, v19, v56
	v_fmac_f32_e32 v86, v18, v41
	v_fmac_f32_e32 v85, v18, v63
	v_fmac_f32_e32 v84, v18, v60
; __device__ __forceinline__ void conv_item(const Params& p, int l, int item) {
;     ...
; #pragma unroll
;         for (int t = 0; t < 32; ++t) {
;             float a = bias;
; #pragma unroll
;             for (int j = 0; j < 31; ++j) a = fmaf(wj[j], win[t + j], a);
;             CV[t * 512 + c] = a;
;         }
	v_fmac_f32_e32 v83, v18, v57
	v_fmac_f32_e32 v82, v18, v54
	v_fmac_f32_e32 v81, v18, v51
	v_fmac_f32_e32 v80, v18, v48
	v_fmac_f32_e32 v79, v18, v45
	v_fmac_f32_e32 v78, v18, v42
	v_fmac_f32_e32 v77, v18, v64
	v_fmac_f32_e32 v76, v18, v61
	v_fmac_f32_e32 v75, v18, v58
	v_fmac_f32_e32 v74, v18, v55
	v_fmac_f32_e32 v73, v18, v52
	v_fmac_f32_e32 v72, v18, v49
	v_fmac_f32_e32 v71, v18, v46
	v_fmac_f32_e32 v70, v18, v43
	v_fmac_f32_e32 v69, v18, v65
	v_fmac_f32_e32 v68, v18, v62
	v_fmac_f32_e32 v67, v18, v59
	v_fmac_f32_e32 v66, v18, v56
	v_fmac_f32_e32 v32, v18, v53
	v_fmac_f32_e32 v87, v17, v41
	v_fmac_f32_e32 v86, v17, v63
	v_fmac_f32_e32 v85, v17, v60
	v_fmac_f32_e32 v84, v17, v57
	v_fmac_f32_e32 v83, v17, v54
	v_fmac_f32_e32 v82, v17, v51
	v_fmac_f32_e32 v81, v17, v48
	v_fmac_f32_e32 v80, v17, v45
	v_fmac_f32_e32 v79, v17, v42
	v_fmac_f32_e32 v78, v17, v64
	v_fmac_f32_e32 v77, v17, v61
	v_fmac_f32_e32 v76, v17, v58
	v_fmac_f32_e32 v75, v17, v55
	v_fmac_f32_e32 v74, v17, v52
	v_fmac_f32_e32 v73, v17, v49
	v_fmac_f32_e32 v72, v17, v46
	v_fmac_f32_e32 v71, v17, v43
	v_fmac_f32_e32 v70, v17, v65
	v_fmac_f32_e32 v69, v17, v62
	v_fmac_f32_e32 v68, v17, v59
	v_fmac_f32_e32 v67, v17, v56
	v_fmac_f32_e32 v66, v17, v53
	v_fmac_f32_e32 v32, v17, v50
	v_fmac_f32_e32 v88, v16, v41
	v_fmac_f32_e32 v87, v16, v63
	v_fmac_f32_e32 v86, v16, v60
	v_fmac_f32_e32 v85, v16, v57
	v_fmac_f32_e32 v84, v16, v54
	v_fmac_f32_e32 v83, v16, v51
	v_fmac_f32_e32 v82, v16, v48
	v_fmac_f32_e32 v81, v16, v45
	v_fmac_f32_e32 v80, v16, v42
	v_fmac_f32_e32 v79, v16, v64
	v_fmac_f32_e32 v78, v16, v61
	v_fmac_f32_e32 v77, v16, v58
	v_fmac_f32_e32 v76, v16, v55
	v_fmac_f32_e32 v75, v16, v52
	v_fmac_f32_e32 v74, v16, v49
	v_fmac_f32_e32 v73, v16, v46
	v_fmac_f32_e32 v72, v16, v43
	v_fmac_f32_e32 v71, v16, v65
	v_fmac_f32_e32 v70, v16, v62
	v_fmac_f32_e32 v69, v16, v59
	v_fmac_f32_e32 v68, v16, v56
	v_fmac_f32_e32 v67, v16, v53
	v_fmac_f32_e32 v66, v16, v50
	v_fmac_f32_e32 v32, v16, v47
	v_fmac_f32_e32 v89, v33, v41
	v_fmac_f32_e32 v88, v33, v63
	v_fmac_f32_e32 v87, v33, v60
	v_fmac_f32_e32 v86, v33, v57
	v_fmac_f32_e32 v85, v33, v54
	v_fmac_f32_e32 v84, v33, v51
	v_fmac_f32_e32 v83, v33, v48
	v_fmac_f32_e32 v82, v33, v45
	v_fmac_f32_e32 v81, v33, v42
	v_fmac_f32_e32 v80, v33, v64
	v_fmac_f32_e32 v79, v33, v61
	v_fmac_f32_e32 v78, v33, v58
	v_fmac_f32_e32 v77, v33, v55
	v_fmac_f32_e32 v76, v33, v52
	v_fmac_f32_e32 v75, v33, v49
	v_fmac_f32_e32 v74, v33, v46
	v_fmac_f32_e32 v73, v33, v43
	v_fmac_f32_e32 v72, v33, v65
	v_fmac_f32_e32 v71, v33, v62
	v_fmac_f32_e32 v70, v33, v59
	v_fmac_f32_e32 v69, v33, v56
	v_fmac_f32_e32 v68, v33, v53
	v_fmac_f32_e32 v67, v33, v50
	v_fmac_f32_e32 v66, v33, v47
	v_fmac_f32_e32 v32, v33, v44
	v_fmac_f32_e32 v91, v31, v41
	v_fmac_f32_e32 v89, v31, v63
	v_fmac_f32_e32 v88, v31, v60
	v_fmac_f32_e32 v87, v31, v57
	v_fmac_f32_e32 v86, v31, v54
	v_fmac_f32_e32 v85, v31, v51
	v_fmac_f32_e32 v84, v31, v48
	v_fmac_f32_e32 v83, v31, v45
	v_fmac_f32_e32 v82, v31, v42
	v_fmac_f32_e32 v81, v31, v64
	v_fmac_f32_e32 v80, v31, v61
	v_fmac_f32_e32 v79, v31, v58
	v_fmac_f32_e32 v78, v31, v55
	v_fmac_f32_e32 v77, v31, v52
	v_fmac_f32_e32 v76, v31, v49
	v_fmac_f32_e32 v75, v31, v46
	v_fmac_f32_e32 v74, v31, v43
	v_fmac_f32_e32 v73, v31, v65
	v_fmac_f32_e32 v72, v31, v62
	v_fmac_f32_e32 v71, v31, v59
	v_fmac_f32_e32 v70, v31, v56
	v_fmac_f32_e32 v69, v31, v53
	v_fmac_f32_e32 v68, v31, v50
	v_fmac_f32_e32 v67, v31, v47
	v_fmac_f32_e32 v66, v31, v44
	v_fmac_f32_e32 v32, v31, v40
	v_fmac_f32_e32 v90, v30, v41
	v_fmac_f32_e32 v91, v30, v63
	v_fmac_f32_e32 v89, v30, v60
	v_fmac_f32_e32 v88, v30, v57
	v_fmac_f32_e32 v87, v30, v54
	v_fmac_f32_e32 v86, v30, v51
	v_fmac_f32_e32 v85, v30, v48
	v_fmac_f32_e32 v84, v30, v45
	v_fmac_f32_e32 v83, v30, v42
	v_fmac_f32_e32 v82, v30, v64
	v_fmac_f32_e32 v81, v30, v61
	v_fmac_f32_e32 v80, v30, v58
	v_fmac_f32_e32 v79, v30, v55
	v_fmac_f32_e32 v78, v30, v52
	v_fmac_f32_e32 v77, v30, v49
	v_fmac_f32_e32 v76, v30, v46
	v_fmac_f32_e32 v75, v30, v43
	v_fmac_f32_e32 v74, v30, v65
	v_fmac_f32_e32 v73, v30, v62
	v_fmac_f32_e32 v72, v30, v59
	v_fmac_f32_e32 v71, v30, v56
	v_fmac_f32_e32 v70, v30, v53
	v_fmac_f32_e32 v69, v30, v50
	v_fmac_f32_e32 v68, v30, v47
	v_fmac_f32_e32 v67, v30, v44
	v_fmac_f32_e32 v66, v30, v40
	v_fmac_f32_e32 v32, v30, v39
	v_fmac_f32_e32 v90, v27, v63
	v_fmac_f32_e32 v91, v27, v60
	v_fmac_f32_e32 v89, v27, v57
	v_fmac_f32_e32 v88, v27, v54
	v_fmac_f32_e32 v87, v27, v51
	v_fmac_f32_e32 v86, v27, v48
	v_fmac_f32_e32 v85, v27, v45
	v_fmac_f32_e32 v84, v27, v42
	v_fmac_f32_e32 v83, v27, v64
	v_fmac_f32_e32 v82, v27, v61
	v_fmac_f32_e32 v81, v27, v58
	v_fmac_f32_e32 v80, v27, v55
	v_fmac_f32_e32 v79, v27, v52
	v_fmac_f32_e32 v78, v27, v49
	v_fmac_f32_e32 v77, v27, v46
	v_fmac_f32_e32 v76, v27, v43
	v_fmac_f32_e32 v75, v27, v65
	v_fmac_f32_e32 v74, v27, v62
	v_fmac_f32_e32 v73, v27, v59
	v_fmac_f32_e32 v72, v27, v56
	v_fmac_f32_e32 v71, v27, v53
	v_fmac_f32_e32 v70, v27, v50
	v_fmac_f32_e32 v69, v27, v47
	v_fmac_f32_e32 v68, v27, v44
	v_fmac_f32_e32 v67, v27, v40
	v_fmac_f32_e32 v66, v27, v39
	v_fmac_f32_e32 v32, v27, v38
	v_fmac_f32_e32 v90, v26, v60
	v_fmac_f32_e32 v91, v26, v57
	v_fmac_f32_e32 v89, v26, v54
	v_fmac_f32_e32 v88, v26, v51
	v_fmac_f32_e32 v87, v26, v48
	v_fmac_f32_e32 v86, v26, v45
	v_fmac_f32_e32 v85, v26, v42
	v_fmac_f32_e32 v84, v26, v64
	v_fmac_f32_e32 v83, v26, v61
	v_fmac_f32_e32 v82, v26, v58
	v_fmac_f32_e32 v81, v26, v55
	v_fmac_f32_e32 v80, v26, v52
	v_fmac_f32_e32 v79, v26, v49
	v_fmac_f32_e32 v78, v26, v46
	v_fmac_f32_e32 v77, v26, v43
	v_fmac_f32_e32 v76, v26, v65
	v_fmac_f32_e32 v75, v26, v62
; __device__ __forceinline__ void conv_item(const Params& p, int l, int item) {
;     ...
;         for (int t = 0; t < 32; ++t) {
;             float a = bias;
; #pragma unroll
;             for (int j = 0; j < 31; ++j) a = fmaf(wj[j], win[t + j], a);
;             CV[t * 512 + c] = a;
;         }
;     }
;     __syncthreads();
;     {
;         const int wv = tid >> 6, lane = tid & 63;
;         const float4 g0 = *reinterpret_cast<const float4*>(p.ln_g + l * 512 + lane * 8);
;         const float4 g1 = *reinterpret_cast<const float4*>(p.ln_g + l * 512 + lane * 8 + 4);
;         const float4 b0 = *reinterpret_cast<const float4*>(p.ln_b + l * 512 + lane * 8);
;         const float4 b1 = *reinterpret_cast<const float4*>(p.ln_b + l * 512 + lane * 8 + 4);
;         const float gg[8] = {g0.x, g0.y, g0.z, g0.w, g1.x, g1.y, g1.z, g1.w};
;         const float bb[8] = {b0.x, b0.y, b0.z, b0.w, b1.x, b1.y, b1.z, b1.w};
; #pragma unroll
;         for (int tt = 0; tt < 4; ++tt) {
;             const int t = wv * 4 + tt;
;             float4 v0 = *reinterpret_cast<const float4*>(CV + t * 512 + lane * 8);
;             float4 v1 = *reinterpret_cast<const float4*>(CV + t * 512 + lane * 8 + 4);
;             float v[8] = {v0.x, v0.y, v0.z, v0.w, v1.x, v1.y, v1.z, v1.w};
;             float s = 0.f, ss = 0.f;
; #pragma unroll
;             for (int i = 0; i < 8; ++i) { s += v[i]; ss += v[i] * v[i]; }
;             s = wave_sum(s); ss = wave_sum(ss);
	v_fmac_f32_e32 v74, v26, v59
	v_fmac_f32_e32 v73, v26, v56
	v_fmac_f32_e32 v72, v26, v53
	v_fmac_f32_e32 v71, v26, v50
	v_fmac_f32_e32 v70, v26, v47
	v_fmac_f32_e32 v69, v26, v44
	v_fmac_f32_e32 v68, v26, v40
	v_fmac_f32_e32 v67, v26, v39
	v_fmac_f32_e32 v66, v26, v38
	v_fmac_f32_e32 v32, v26, v37
	v_ashrrev_i32_e32 v26, 4, v29
	v_and_b32_e32 v4, -4, v26
	v_add_u32_e32 v16, s3, v4
	v_ashrrev_i32_e32 v17, 31, v16
	v_lshlrev_b64 v[0:1], 13, v[16:17]
	v_lshl_add_u64 v[0:1], s[78:79], 0, v[0:1]
	v_lshl_add_u64 v[0:1], v[0:1], 0, v[128:129]
	v_fmac_f32_e32 v90, v25, v57
	v_fmac_f32_e32 v91, v25, v54
	v_fmac_f32_e32 v89, v25, v51
	v_fmac_f32_e32 v88, v25, v48
	v_fmac_f32_e32 v87, v25, v45
	v_fmac_f32_e32 v86, v25, v42
	v_fmac_f32_e32 v85, v25, v64
	v_fmac_f32_e32 v84, v25, v61
	v_fmac_f32_e32 v83, v25, v58
	v_fmac_f32_e32 v82, v25, v55
	v_fmac_f32_e32 v81, v25, v52
	v_fmac_f32_e32 v80, v25, v49
	v_fmac_f32_e32 v79, v25, v46
	v_fmac_f32_e32 v78, v25, v43
	v_fmac_f32_e32 v77, v25, v65
	v_fmac_f32_e32 v76, v25, v62
	v_fmac_f32_e32 v75, v25, v59
	v_fmac_f32_e32 v74, v25, v56
	v_fmac_f32_e32 v73, v25, v53
	v_fmac_f32_e32 v72, v25, v50
	v_fmac_f32_e32 v71, v25, v47
	v_fmac_f32_e32 v70, v25, v44
	v_fmac_f32_e32 v69, v25, v40
	v_fmac_f32_e32 v68, v25, v39
	v_fmac_f32_e32 v67, v25, v38
	v_fmac_f32_e32 v66, v25, v37
	v_fmac_f32_e32 v32, v25, v35
	v_add_co_u32_e32 v2, vcc, s0, v0
	v_fmac_f32_e32 v90, v24, v54
	v_fmac_f32_e32 v91, v24, v51
	v_fmac_f32_e32 v89, v24, v48
	v_fmac_f32_e32 v88, v24, v45
	v_fmac_f32_e32 v87, v24, v42
	v_fmac_f32_e32 v86, v24, v64
	v_fmac_f32_e32 v85, v24, v61
	v_fmac_f32_e32 v84, v24, v58
	v_fmac_f32_e32 v83, v24, v55
	v_fmac_f32_e32 v82, v24, v52
	v_fmac_f32_e32 v81, v24, v49
	v_fmac_f32_e32 v80, v24, v46
	v_fmac_f32_e32 v79, v24, v43
	v_fmac_f32_e32 v78, v24, v65
	v_fmac_f32_e32 v77, v24, v62
	v_fmac_f32_e32 v76, v24, v59
	v_fmac_f32_e32 v75, v24, v56
	v_fmac_f32_e32 v74, v24, v53
	v_fmac_f32_e32 v73, v24, v50
	v_fmac_f32_e32 v72, v24, v47
	v_fmac_f32_e32 v71, v24, v44
	v_fmac_f32_e32 v70, v24, v40
	v_fmac_f32_e32 v69, v24, v39
	v_fmac_f32_e32 v68, v24, v38
	v_fmac_f32_e32 v67, v24, v37
	v_fmac_f32_e32 v66, v24, v35
	v_fmac_f32_e32 v32, v24, v34
	v_addc_co_u32_e32 v3, vcc, 0, v1, vcc
	ds_write2st64_b32 v36, v90, v91 offset0:40 offset1:48
	ds_write2st64_b32 v36, v89, v88 offset0:56 offset1:64
	ds_write2st64_b32 v36, v87, v86 offset0:72 offset1:80
	ds_write2st64_b32 v36, v85, v84 offset0:88 offset1:96
	ds_write2st64_b32 v36, v83, v82 offset0:104 offset1:112
	ds_write2st64_b32 v36, v81, v80 offset0:120 offset1:128
	ds_write2st64_b32 v36, v79, v78 offset0:136 offset1:144
	ds_write2st64_b32 v36, v77, v76 offset0:152 offset1:160
	ds_write2st64_b32 v36, v75, v74 offset0:168 offset1:176
	ds_write2st64_b32 v36, v73, v72 offset0:184 offset1:192
	ds_write2st64_b32 v36, v71, v70 offset0:200 offset1:208
	ds_write2st64_b32 v36, v69, v68 offset0:216 offset1:224
	ds_write2st64_b32 v36, v67, v66 offset0:232 offset1:240
	ds_write_b32 v36, v32 offset:63488
	s_waitcnt lgkmcnt(0)
	s_barrier
	s_waitcnt vmcnt(0)
	v_mov_b32_e32 v30, v140
	v_mov_b32_e32 v31, v141
	v_mov_b32_e32 v32, v142
	v_mov_b32_e32 v33, v143
	v_and_b32_e32 v2, 64, v213
	v_add_u32_e32 v2, 64, v2
	v_xor_b32_e32 v3, 32, v213
	v_cmp_lt_i32_e32 vcc, v3, v2
	v_lshlrev_b32_e32 v12, 2, v28
	v_add_u32_e32 v27, 0, v12
	v_cndmask_b32_e32 v3, v213, v3, vcc
	v_lshlrev_b32_e32 v25, 2, v3
	v_xor_b32_e32 v3, 16, v213
	v_cmp_lt_i32_e32 vcc, v3, v2
	v_lshl_add_u32 v17, v4, 11, v27
	v_lshl_add_u64 v[18:19], v[0:1], 0, s[10:11]
	v_cndmask_b32_e32 v3, v213, v3, vcc
	v_lshlrev_b32_e32 v24, 2, v3
	v_xor_b32_e32 v3, 8, v213
	v_cmp_lt_i32_e32 vcc, v3, v2
	ds_read_b128 v[34:37], v17 offset:63488
	ds_read_b128 v[38:41], v17 offset:63504
	v_cndmask_b32_e32 v3, v213, v3, vcc
	v_lshlrev_b32_e32 v23, 2, v3
	v_xor_b32_e32 v3, 4, v213
	v_cmp_lt_i32_e32 vcc, v3, v2
	v_mov_b32_e32 v50, v129
	s_waitcnt lgkmcnt(1)
	v_mov_b32_e32 v51, v35
	v_cndmask_b32_e32 v3, v213, v3, vcc
	v_lshlrev_b32_e32 v22, 2, v3
	v_xor_b32_e32 v3, 2, v213
	v_cmp_lt_i32_e32 vcc, v3, v2
	v_pk_mul_f32 v[48:49], v[34:35], v[34:35]
	v_pk_add_f32 v[50:51], v[34:35], v[50:51]
	v_cndmask_b32_e32 v3, v213, v3, vcc
	v_lshlrev_b32_e32 v21, 2, v3
	v_xor_b32_e32 v3, 1, v213
	v_cmp_lt_i32_e32 vcc, v3, v2
	v_pk_mov_b32 v[50:51], v[48:49], v[50:51] op_sel:[1,0]
	v_mov_b32_e32 v49, v35
	v_cndmask_b32_e32 v2, v213, v3, vcc
	v_lshlrev_b32_e32 v20, 2, v2
	global_load_dwordx4 v[0:3], v12, s[4:5] offset:16
	global_load_dwordx4 v[8:11], v12, s[4:5]
	global_load_dwordx4 v[4:7], v12, s[6:7] offset:16
	s_nop 0
	global_load_dwordx4 v[12:15], v12, s[6:7]
	v_pk_add_f32 v[48:49], v[50:51], v[48:49]
	v_mov_b32_e32 v51, v36
	s_waitcnt lgkmcnt(0)
	v_pk_mul_f32 v[44:45], v[38:39], v[38:39]
	v_pk_mul_f32 v[28:29], v[40:41], v[40:41]
	v_or_b32_e32 v26, 3, v26
	s_waitcnt vmcnt(4)
	v_lshlrev_b32_e32 v46, 16, v32
	v_and_b32_e32 v47, 0xffff0000, v32
	v_mul_f32_e32 v32, 0xbfb8aa3b, v46
	v_lshlrev_b32_e32 v42, 16, v33
	v_and_b32_e32 v43, 0xffff0000, v33
	v_exp_f32_e32 v52, v32
	v_pk_mul_f32 v[32:33], v[36:37], v[36:37]
	s_nop 0
	v_mov_b32_e32 v50, v32
	v_pk_add_f32 v[48:49], v[48:49], v[50:51]
	v_mov_b32_e32 v32, v33
	v_mov_b32_e32 v33, v37
	v_pk_add_f32 v[32:33], v[48:49], v[32:33]
	v_mov_b32_e32 v48, v44
	v_mov_b32_e32 v49, v38
	v_pk_add_f32 v[32:33], v[32:33], v[48:49]
	v_mov_b32_e32 v44, v45
	v_mov_b32_e32 v45, v39
	v_pk_add_f32 v[32:33], v[32:33], v[44:45]
	v_mov_b32_e32 v44, v28
	v_mov_b32_e32 v45, v40
	v_pk_add_f32 v[32:33], v[32:33], v[44:45]
	v_mov_b32_e32 v28, v29
	v_mov_b32_e32 v29, v41
	v_pk_add_f32 v[28:29], v[32:33], v[28:29]
	ds_bpermute_b32 v33, v25, v29
	ds_bpermute_b32 v32, v25, v28
	v_lshlrev_b32_e32 v48, 16, v31
	v_and_b32_e32 v49, 0xffff0000, v31
	v_mul_f32_e32 v31, 0xbfb8aa3b, v48
	v_mul_f32_e32 v45, 0xbfb8aa3b, v47
	s_waitcnt lgkmcnt(0)
; __device__ __forceinline__ float sigmoidf_(float x) { return __builtin_amdgcn_rcpf(1.0f + __expf(-x)); }
; __device__ __forceinline__ float siluf_(float x) { return x * sigmoidf_(x); }
; __device__ __forceinline__ void conv_item(const Params& p, int l, int item) {
;     ...
; #pragma unroll
;             for (int i = 0; i < 8; ++i) { s += v[i]; ss += v[i] * v[i]; }
;             s = wave_sum(s); ss = wave_sum(ss);
;             const float mean = s * (1.0f / 512.f);
;             const float var = fmaxf(ss * (1.0f / 512.f) - mean * mean, 0.f);
;             const float rstd = rsqrtf(var + 1e-5f);
;             bf16_t* gp = P1 + (long)(R0 + t) * P1W + 2048 + lane * 8;
;             uint4 gv = ld_nt_u4(gp);
;             const float gt[8] = {bflo(gv.x), bfhi(gv.x), bflo(gv.y), bfhi(gv.y), bflo(gv.z), bfhi(gv.z), bflo(gv.w), bfhi(gv.w)};
;             float y[8];
; #pragma unroll
;             for (int i = 0; i < 8; ++i) {
;                 float u = (v[i] - mean) * rstd * gg[i] + bb[i];
;                 y[i] = u * sigmoidf_(u) * siluf_(gt[i]);
;             }
;             uint4 o; o.x = pk2(y[0], y[1]); o.y = pk2(y[2], y[3]); o.z = pk2(y[4], y[5]); o.w = pk2(y[6], y[7]);
;             st16_wt(gp, o);
	v_pk_add_f32 v[28:29], v[28:29], v[32:33]
	ds_bpermute_b32 v33, v24, v29
	ds_bpermute_b32 v32, v24, v28
	v_exp_f32_e32 v31, v31
	v_mul_f32_e32 v50, 0xbfb8aa3b, v49
	v_exp_f32_e32 v45, v45
	v_exp_f32_e32 v51, v50
	s_waitcnt lgkmcnt(0)
	v_pk_add_f32 v[28:29], v[28:29], v[32:33]
	ds_bpermute_b32 v33, v23, v29
	ds_bpermute_b32 v32, v23, v28
	v_add_f32_e32 v31, 1.0, v31
	v_add_f32_e32 v44, 1.0, v52
	v_add_f32_e32 v45, 1.0, v45
	v_rcp_f32_e32 v50, v31
	s_waitcnt lgkmcnt(0)
	v_pk_add_f32 v[28:29], v[28:29], v[32:33]
	ds_bpermute_b32 v33, v22, v29
	ds_bpermute_b32 v32, v22, v28
	v_add_f32_e32 v31, 1.0, v51
	v_rcp_f32_e32 v44, v44
	v_rcp_f32_e32 v45, v45
	v_rcp_f32_e32 v51, v31
	s_waitcnt lgkmcnt(0)
	v_pk_add_f32 v[28:29], v[28:29], v[32:33]
	ds_bpermute_b32 v33, v21, v29
	ds_bpermute_b32 v32, v21, v28
	v_pk_mul_f32 v[44:45], v[44:45], v[46:47]
	v_pk_mul_f32 v[46:47], v[50:51], v[48:49]
	v_lshlrev_b32_e32 v48, 16, v30
	v_and_b32_e32 v49, 0xffff0000, v30
	s_waitcnt lgkmcnt(0)
	v_pk_add_f32 v[28:29], v[28:29], v[32:33]
	ds_bpermute_b32 v31, v20, v29
	ds_bpermute_b32 v30, v20, v28
	v_mul_f32_e32 v32, 0xbfb8aa3b, v48
	v_exp_f32_e32 v32, v32
	v_mul_f32_e32 v33, 0xbfb8aa3b, v49
	v_exp_f32_e32 v33, v33
	s_waitcnt lgkmcnt(0)
	v_pk_add_f32 v[28:29], v[28:29], v[30:31]
	v_add_f32_e32 v33, 1.0, v33
	v_pk_mul_f32 v[28:29], v[28:29], s[12:13] op_sel_hi:[1,0]
	s_nop 0
	v_fma_f32 v30, -v29, v29, v28
	v_max_f32_e32 v30, 0, v30
	v_add_f32_e32 v30, 0x3727c5ac, v30
	v_mul_f32_e32 v31, 0x4b800000, v30
	v_cmp_gt_f32_e32 vcc, s94, v30
	v_pk_add_f32 v[34:35], v[34:35], v[28:29] op_sel:[0,1] neg_lo:[0,1] neg_hi:[0,1]
	v_pk_add_f32 v[36:37], v[36:37], v[28:29] op_sel:[0,1] neg_lo:[0,1] neg_hi:[0,1]
	v_cndmask_b32_e32 v30, v30, v31, vcc
	v_rsq_f32_e32 v31, v30
	v_add_f32_e32 v30, 1.0, v32
	v_rcp_f32_e32 v30, v30
	v_mul_f32_e32 v32, 0x45800000, v31
	v_cndmask_b32_e32 v32, v31, v32, vcc
	v_pk_mul_f32 v[34:35], v[34:35], v[32:33] op_sel_hi:[1,0]
	s_waitcnt vmcnt(0)
	v_pk_fma_f32 v[34:35], v[8:9], v[34:35], v[12:13]
	s_nop 0
	v_mul_f32_e32 v31, 0xbfb8aa3b, v34
	v_exp_f32_e32 v50, v31
	v_mul_f32_e32 v31, 0xbfb8aa3b, v35
	v_exp_f32_e32 v51, v31
	v_rcp_f32_e32 v31, v33
	v_add_f32_e32 v33, 1.0, v50
	v_rcp_f32_e32 v50, v33
	v_add_f32_e32 v33, 1.0, v51
	v_pk_mul_f32 v[36:37], v[36:37], v[32:33] op_sel_hi:[1,0]
	v_pk_mul_f32 v[30:31], v[30:31], v[48:49]
	v_pk_fma_f32 v[36:37], v[10:11], v[36:37], v[14:15]
	s_nop 0
	v_mul_f32_e32 v51, 0xbfb8aa3b, v36
	v_exp_f32_e32 v52, v51
	v_mul_f32_e32 v51, 0xbfb8aa3b, v37
	v_exp_f32_e32 v53, v51
	v_rcp_f32_e32 v51, v33
	v_add_f32_e32 v33, 1.0, v52
	v_rcp_f32_e32 v52, v33
	v_add_f32_e32 v33, 1.0, v53
	v_rcp_f32_e32 v53, v33
	v_pk_mul_f32 v[34:35], v[34:35], v[50:51]
	v_mov_b32_e32 v50, v129
	v_pk_mul_f32 v[30:31], v[30:31], v[34:35]
	v_pk_mul_f32 v[34:35], v[36:37], v[52:53]
	v_pk_add_f32 v[36:37], v[38:39], v[28:29] op_sel:[0,1] neg_lo:[0,1] neg_hi:[0,1]
	v_pk_add_f32 v[28:29], v[40:41], v[28:29] op_sel:[0,1] neg_lo:[0,1] neg_hi:[0,1]
	v_pk_mul_f32 v[36:37], v[36:37], v[32:33] op_sel_hi:[1,0]
	v_pk_mul_f32 v[34:35], v[46:47], v[34:35]
	v_pk_fma_f32 v[36:37], v[0:1], v[36:37], v[4:5]
	s_nop 0
	v_mul_f32_e32 v33, 0xbfb8aa3b, v36
	v_exp_f32_e32 v33, v33
	v_mul_f32_e32 v38, 0xbfb8aa3b, v37
	v_exp_f32_e32 v39, v38
	v_add_f32_e32 v33, 1.0, v33
	v_rcp_f32_e32 v38, v33
	v_add_f32_e32 v33, 1.0, v39
	v_mul_f32_e32 v39, 0xbfb8aa3b, v42
	v_exp_f32_e32 v40, v39
	v_pk_mul_f32 v[28:29], v[28:29], v[32:33] op_sel_hi:[1,0]
	v_rcp_f32_e32 v39, v33
	v_pk_fma_f32 v[28:29], v[2:3], v[28:29], v[6:7]
	v_add_f32_e32 v33, 1.0, v40
	v_mul_f32_e32 v40, 0xbfb8aa3b, v29
	v_mul_f32_e32 v32, 0xbfb8aa3b, v28
	v_exp_f32_e32 v41, v40
	v_mul_f32_e32 v40, 0xbfb8aa3b, v43
	v_exp_f32_e32 v32, v32
	v_exp_f32_e32 v46, v40
	v_rcp_f32_e32 v40, v33
	v_add_f32_e32 v33, 1.0, v41
	v_add_f32_e32 v32, 1.0, v32
	v_add_f32_e32 v41, 1.0, v46
	v_rcp_f32_e32 v32, v32
	v_rcp_f32_e32 v33, v33
	v_rcp_f32_e32 v41, v41
	v_pk_mul_f32 v[36:37], v[36:37], v[38:39]
	v_pk_mul_f32 v[28:29], v[28:29], v[32:33]
	v_pk_mul_f32 v[32:33], v[40:41], v[42:43]
	v_pk_mul_f32 v[36:37], v[44:45], v[36:37]
	v_pk_mul_f32 v[32:33], v[32:33], v[28:29]
	v_cvt_pk_bf16_f32 v28, v30, v31
	v_cvt_pk_bf16_f32 v29, v34, v35
	v_cvt_pk_bf16_f32 v30, v36, v37
	v_cvt_pk_bf16_f32 v31, v32, v33
	global_store_dwordx4 v[18:19], v[28:31], off sc1
	s_nop 1
	v_add_u32_e32 v18, 1, v16
	v_ashrrev_i32_e32 v19, 31, v18
	v_lshlrev_b64 v[18:19], 13, v[18:19]
	v_lshl_add_u64 v[18:19], s[78:79], 0, v[18:19]
	v_lshl_add_u64 v[18:19], v[18:19], 0, v[128:129]
	v_add_co_u32_e32 v28, vcc, s0, v18
	v_add_u32_e32 v36, 0x800, v17
	s_nop 0
	v_addc_co_u32_e32 v29, vcc, 0, v19, vcc
	v_mov_b32_e32 v28, v144
	v_mov_b32_e32 v29, v145
	v_mov_b32_e32 v30, v146
	v_mov_b32_e32 v31, v147
	ds_read_b128 v[32:35], v36 offset:63504
	ds_read_b128 v[36:39], v36 offset:63488
	v_lshl_add_u64 v[18:19], v[18:19], 0, s[10:11]
	s_waitcnt lgkmcnt(1)
	v_pk_mul_f32 v[44:45], v[32:33], v[32:33]
	s_waitcnt lgkmcnt(0)
	v_mov_b32_e32 v51, v37
	v_pk_mul_f32 v[48:49], v[36:37], v[36:37]
	v_pk_add_f32 v[50:51], v[36:37], v[50:51]
	v_pk_mul_f32 v[40:41], v[34:35], v[34:35]
	v_pk_mov_b32 v[50:51], v[48:49], v[50:51] op_sel:[1,0]
	v_mov_b32_e32 v49, v37
	v_pk_add_f32 v[48:49], v[50:51], v[48:49]
	v_mov_b32_e32 v51, v38
	v_lshlrev_b32_e32 v46, 16, v30
	v_and_b32_e32 v47, 0xffff0000, v30
	v_mul_f32_e32 v30, 0xbfb8aa3b, v46
	v_lshlrev_b32_e32 v42, 16, v31
	v_and_b32_e32 v43, 0xffff0000, v31
	v_exp_f32_e32 v52, v30
	v_pk_mul_f32 v[30:31], v[38:39], v[38:39]
	s_nop 0
	v_mov_b32_e32 v50, v30
	v_pk_add_f32 v[48:49], v[48:49], v[50:51]
	v_mov_b32_e32 v30, v31
	v_mov_b32_e32 v31, v39
	v_pk_add_f32 v[30:31], v[48:49], v[30:31]
	v_mov_b32_e32 v48, v44
	v_mov_b32_e32 v49, v32
	v_pk_add_f32 v[30:31], v[30:31], v[48:49]
	v_mov_b32_e32 v44, v45
	v_mov_b32_e32 v45, v33
	v_pk_add_f32 v[30:31], v[30:31], v[44:45]
	v_mov_b32_e32 v44, v40
	v_mov_b32_e32 v45, v34
	v_pk_add_f32 v[30:31], v[30:31], v[44:45]
	v_mov_b32_e32 v40, v41
	v_mov_b32_e32 v41, v35
	v_pk_add_f32 v[30:31], v[30:31], v[40:41]
	ds_bpermute_b32 v41, v25, v31
	ds_bpermute_b32 v40, v25, v30
	v_lshlrev_b32_e32 v48, 16, v29
	v_and_b32_e32 v49, 0xffff0000, v29
	v_mul_f32_e32 v29, 0xbfb8aa3b, v48
	v_mul_f32_e32 v45, 0xbfb8aa3b, v47
	s_waitcnt lgkmcnt(0)
; __device__ __forceinline__ float sigmoidf_(float x) { return __builtin_amdgcn_rcpf(1.0f + __expf(-x)); }
; __device__ __forceinline__ float siluf_(float x) { return x * sigmoidf_(x); }
; __device__ __forceinline__ void conv_item(const Params& p, int l, int item) {
;     ...
; #pragma unroll
;             for (int i = 0; i < 8; ++i) { s += v[i]; ss += v[i] * v[i]; }
;             s = wave_sum(s); ss = wave_sum(ss);
;             const float mean = s * (1.0f / 512.f);
;             const float var = fmaxf(ss * (1.0f / 512.f) - mean * mean, 0.f);
;             const float rstd = rsqrtf(var + 1e-5f);
;             bf16_t* gp = P1 + (long)(R0 + t) * P1W + 2048 + lane * 8;
;             uint4 gv = ld_nt_u4(gp);
;             const float gt[8] = {bflo(gv.x), bfhi(gv.x), bflo(gv.y), bfhi(gv.y), bflo(gv.z), bfhi(gv.z), bflo(gv.w), bfhi(gv.w)};
;             float y[8];
; #pragma unroll
;             for (int i = 0; i < 8; ++i) {
;                 float u = (v[i] - mean) * rstd * gg[i] + bb[i];
;                 y[i] = u * sigmoidf_(u) * siluf_(gt[i]);
;             }
;             uint4 o; o.x = pk2(y[0], y[1]); o.y = pk2(y[2], y[3]); o.z = pk2(y[4], y[5]); o.w = pk2(y[6], y[7]);
;             st16_wt(gp, o);
	v_pk_add_f32 v[30:31], v[30:31], v[40:41]
	ds_bpermute_b32 v41, v24, v31
	ds_bpermute_b32 v40, v24, v30
	v_exp_f32_e32 v29, v29
	v_mul_f32_e32 v50, 0xbfb8aa3b, v49
	v_exp_f32_e32 v45, v45
	v_exp_f32_e32 v51, v50
	s_waitcnt lgkmcnt(0)
	v_pk_add_f32 v[30:31], v[30:31], v[40:41]
	ds_bpermute_b32 v41, v23, v31
	ds_bpermute_b32 v40, v23, v30
	v_add_f32_e32 v29, 1.0, v29
	v_add_f32_e32 v44, 1.0, v52
	v_add_f32_e32 v45, 1.0, v45
	v_rcp_f32_e32 v50, v29
	s_waitcnt lgkmcnt(0)
	v_pk_add_f32 v[30:31], v[30:31], v[40:41]
	ds_bpermute_b32 v41, v22, v31
	ds_bpermute_b32 v40, v22, v30
	v_add_f32_e32 v29, 1.0, v51
	v_rcp_f32_e32 v44, v44
	v_rcp_f32_e32 v45, v45
	v_rcp_f32_e32 v51, v29
	s_waitcnt lgkmcnt(0)
	v_pk_add_f32 v[30:31], v[30:31], v[40:41]
	ds_bpermute_b32 v41, v21, v31
	ds_bpermute_b32 v40, v21, v30
	v_pk_mul_f32 v[44:45], v[44:45], v[46:47]
	v_pk_mul_f32 v[46:47], v[50:51], v[48:49]
	v_lshlrev_b32_e32 v48, 16, v28
	v_and_b32_e32 v49, 0xffff0000, v28
	s_waitcnt lgkmcnt(0)
	v_pk_add_f32 v[28:29], v[30:31], v[40:41]
	ds_bpermute_b32 v31, v20, v29
	ds_bpermute_b32 v30, v20, v28
	v_mul_f32_e32 v40, 0xbfb8aa3b, v48
	v_exp_f32_e32 v40, v40
	v_mul_f32_e32 v41, 0xbfb8aa3b, v49
	v_exp_f32_e32 v41, v41
	s_waitcnt lgkmcnt(0)
	v_pk_add_f32 v[28:29], v[28:29], v[30:31]
	v_add_f32_e32 v41, 1.0, v41
	v_pk_mul_f32 v[28:29], v[28:29], s[12:13] op_sel_hi:[1,0]
	s_nop 0
	v_fma_f32 v30, -v29, v29, v28
	v_max_f32_e32 v30, 0, v30
	v_add_f32_e32 v30, 0x3727c5ac, v30
	v_mul_f32_e32 v31, 0x4b800000, v30
	v_cmp_gt_f32_e32 vcc, s94, v30
	v_pk_add_f32 v[36:37], v[36:37], v[28:29] op_sel:[0,1] neg_lo:[0,1] neg_hi:[0,1]
	v_pk_add_f32 v[38:39], v[38:39], v[28:29] op_sel:[0,1] neg_lo:[0,1] neg_hi:[0,1]
	v_cndmask_b32_e32 v30, v30, v31, vcc
	v_rsq_f32_e32 v31, v30
	v_add_f32_e32 v30, 1.0, v40
	v_rcp_f32_e32 v30, v30
	v_pk_add_f32 v[32:33], v[32:33], v[28:29] op_sel:[0,1] neg_lo:[0,1] neg_hi:[0,1]
	v_mul_f32_e32 v40, 0x45800000, v31
	v_cndmask_b32_e32 v40, v31, v40, vcc
	v_pk_mul_f32 v[36:37], v[36:37], v[40:41] op_sel_hi:[1,0]
	v_pk_add_f32 v[28:29], v[34:35], v[28:29] op_sel:[0,1] neg_lo:[0,1] neg_hi:[0,1]
	v_pk_fma_f32 v[36:37], v[8:9], v[36:37], v[12:13]
	v_mul_f32_e32 v35, 0xbfb8aa3b, v42
	v_mul_f32_e32 v31, 0xbfb8aa3b, v36
	v_exp_f32_e32 v50, v31
	v_mul_f32_e32 v31, 0xbfb8aa3b, v37
	v_exp_f32_e32 v51, v31
	v_rcp_f32_e32 v31, v41
	v_add_f32_e32 v41, 1.0, v50
	v_rcp_f32_e32 v50, v41
	v_add_f32_e32 v41, 1.0, v51
	v_pk_mul_f32 v[38:39], v[38:39], v[40:41] op_sel_hi:[1,0]
	v_pk_mul_f32 v[30:31], v[30:31], v[48:49]
	v_pk_fma_f32 v[38:39], v[10:11], v[38:39], v[14:15]
	v_exp_f32_e32 v35, v35
	v_mul_f32_e32 v51, 0xbfb8aa3b, v38
	v_exp_f32_e32 v52, v51
	v_mul_f32_e32 v51, 0xbfb8aa3b, v39
	v_exp_f32_e32 v53, v51
	v_rcp_f32_e32 v51, v41
	v_add_f32_e32 v41, 1.0, v52
	v_rcp_f32_e32 v52, v41
	v_add_f32_e32 v41, 1.0, v53
	v_rcp_f32_e32 v53, v41
	v_pk_mul_f32 v[28:29], v[28:29], v[40:41] op_sel_hi:[1,0]
	v_pk_mul_f32 v[32:33], v[32:33], v[40:41] op_sel_hi:[1,0]
	v_pk_fma_f32 v[28:29], v[2:3], v[28:29], v[6:7]
	v_pk_mul_f32 v[36:37], v[36:37], v[50:51]
	v_pk_fma_f32 v[32:33], v[0:1], v[32:33], v[4:5]
	v_mul_f32_e32 v40, 0xbfb8aa3b, v29
	v_pk_mul_f32 v[30:31], v[30:31], v[36:37]
	v_pk_mul_f32 v[36:37], v[38:39], v[52:53]
	v_mul_f32_e32 v38, 0xbfb8aa3b, v32
	v_mul_f32_e32 v39, 0xbfb8aa3b, v33
	v_mul_f32_e32 v34, 0xbfb8aa3b, v28
	v_exp_f32_e32 v41, v40
	v_mul_f32_e32 v40, 0xbfb8aa3b, v43
	v_exp_f32_e32 v38, v38
	v_exp_f32_e32 v39, v39
	v_pk_mul_f32 v[36:37], v[46:47], v[36:37]
	v_exp_f32_e32 v34, v34
	v_exp_f32_e32 v46, v40
	v_add_f32_e32 v35, 1.0, v35
	v_add_f32_e32 v38, 1.0, v38
	v_add_f32_e32 v39, 1.0, v39
	v_add_f32_e32 v34, 1.0, v34
	v_rcp_f32_e32 v40, v35
	v_add_f32_e32 v35, 1.0, v41
	v_add_f32_e32 v41, 1.0, v46
	v_rcp_f32_e32 v38, v38
	v_rcp_f32_e32 v39, v39
	v_rcp_f32_e32 v34, v34
	v_rcp_f32_e32 v35, v35
	v_rcp_f32_e32 v41, v41
	v_pk_mul_f32 v[32:33], v[32:33], v[38:39]
	v_mov_b32_e32 v48, v129
	v_pk_mul_f32 v[28:29], v[28:29], v[34:35]
	v_pk_mul_f32 v[34:35], v[40:41], v[42:43]
	v_pk_mul_f32 v[32:33], v[44:45], v[32:33]
	v_pk_mul_f32 v[34:35], v[34:35], v[28:29]
	v_cvt_pk_bf16_f32 v28, v30, v31
	v_cvt_pk_bf16_f32 v29, v36, v37
	v_cvt_pk_bf16_f32 v30, v32, v33
	v_cvt_pk_bf16_f32 v31, v34, v35
	global_store_dwordx4 v[18:19], v[28:31], off sc1
	s_nop 1
	v_add_u32_e32 v18, 2, v16
	v_ashrrev_i32_e32 v19, 31, v18
	v_lshlrev_b64 v[18:19], 13, v[18:19]
	v_lshl_add_u64 v[18:19], s[78:79], 0, v[18:19]
	v_lshl_add_u64 v[18:19], v[18:19], 0, v[128:129]
	v_add_co_u32_e32 v28, vcc, s0, v18
	v_add_u32_e32 v16, 0x1000, v17
	s_nop 0
	v_addc_co_u32_e32 v29, vcc, 0, v19, vcc
	v_mov_b32_e32 v28, v148
	v_mov_b32_e32 v29, v149
	v_mov_b32_e32 v30, v150
	v_mov_b32_e32 v31, v151
	ds_read_b128 v[32:35], v16 offset:63504
	ds_read_b128 v[36:39], v16 offset:63488
	v_lshl_add_u64 v[16:17], v[18:19], 0, s[10:11]
	s_waitcnt lgkmcnt(1)
	v_pk_mul_f32 v[42:43], v[32:33], v[32:33]
	s_waitcnt lgkmcnt(0)
	v_mov_b32_e32 v49, v37
	v_pk_mul_f32 v[46:47], v[36:37], v[36:37]
	v_pk_add_f32 v[48:49], v[36:37], v[48:49]
	v_pk_mul_f32 v[18:19], v[34:35], v[34:35]
	v_pk_mov_b32 v[48:49], v[46:47], v[48:49] op_sel:[1,0]
	v_mov_b32_e32 v47, v37
	v_pk_add_f32 v[46:47], v[48:49], v[46:47]
	v_mov_b32_e32 v49, v38
	v_lshlrev_b32_e32 v44, 16, v30
	v_and_b32_e32 v45, 0xffff0000, v30
	v_mul_f32_e32 v30, 0xbfb8aa3b, v44
	v_lshlrev_b32_e32 v40, 16, v31
	v_and_b32_e32 v41, 0xffff0000, v31
	v_exp_f32_e32 v50, v30
	v_pk_mul_f32 v[30:31], v[38:39], v[38:39]
	s_nop 0
	v_mov_b32_e32 v48, v30
	v_pk_add_f32 v[46:47], v[46:47], v[48:49]
	v_mov_b32_e32 v30, v31
	v_mov_b32_e32 v31, v39
	v_pk_add_f32 v[30:31], v[46:47], v[30:31]
	v_mov_b32_e32 v46, v42
	v_mov_b32_e32 v47, v32
	v_pk_add_f32 v[30:31], v[30:31], v[46:47]
	v_mov_b32_e32 v42, v43
	v_mov_b32_e32 v43, v33
	v_pk_add_f32 v[30:31], v[30:31], v[42:43]
	v_mov_b32_e32 v42, v18
	v_mov_b32_e32 v43, v34
	v_pk_add_f32 v[30:31], v[30:31], v[42:43]
	v_mov_b32_e32 v18, v19
	v_mov_b32_e32 v19, v35
	v_pk_add_f32 v[18:19], v[30:31], v[18:19]
	ds_bpermute_b32 v31, v25, v19
	ds_bpermute_b32 v30, v25, v18
	v_lshlrev_b32_e32 v46, 16, v29
	v_and_b32_e32 v47, 0xffff0000, v29
	v_mul_f32_e32 v29, 0xbfb8aa3b, v46
	v_mul_f32_e32 v43, 0xbfb8aa3b, v45
	s_waitcnt lgkmcnt(0)
; __device__ __forceinline__ float sigmoidf_(float x) { return __builtin_amdgcn_rcpf(1.0f + __expf(-x)); }
; __device__ __forceinline__ float siluf_(float x) { return x * sigmoidf_(x); }
; __device__ __forceinline__ void conv_item(const Params& p, int l, int item) {
;     ...
; #pragma unroll
;             for (int i = 0; i < 8; ++i) { s += v[i]; ss += v[i] * v[i]; }
;             s = wave_sum(s); ss = wave_sum(ss);
;             const float mean = s * (1.0f / 512.f);
;             const float var = fmaxf(ss * (1.0f / 512.f) - mean * mean, 0.f);
;             const float rstd = rsqrtf(var + 1e-5f);
;             bf16_t* gp = P1 + (long)(R0 + t) * P1W + 2048 + lane * 8;
;             uint4 gv = ld_nt_u4(gp);
;             const float gt[8] = {bflo(gv.x), bfhi(gv.x), bflo(gv.y), bfhi(gv.y), bflo(gv.z), bfhi(gv.z), bflo(gv.w), bfhi(gv.w)};
;             float y[8];
; #pragma unroll
;             for (int i = 0; i < 8; ++i) {
;                 float u = (v[i] - mean) * rstd * gg[i] + bb[i];
;                 y[i] = u * sigmoidf_(u) * siluf_(gt[i]);
;             }
;             uint4 o; o.x = pk2(y[0], y[1]); o.y = pk2(y[2], y[3]); o.z = pk2(y[4], y[5]); o.w = pk2(y[6], y[7]);
;             st16_wt(gp, o);
	v_pk_add_f32 v[18:19], v[18:19], v[30:31]
	ds_bpermute_b32 v31, v24, v19
	ds_bpermute_b32 v30, v24, v18
	v_exp_f32_e32 v29, v29
	v_mul_f32_e32 v48, 0xbfb8aa3b, v47
	v_exp_f32_e32 v43, v43
	v_exp_f32_e32 v49, v48
	s_waitcnt lgkmcnt(0)
	v_pk_add_f32 v[18:19], v[18:19], v[30:31]
	ds_bpermute_b32 v31, v23, v19
	ds_bpermute_b32 v30, v23, v18
	v_add_f32_e32 v29, 1.0, v29
	v_add_f32_e32 v42, 1.0, v50
	v_add_f32_e32 v43, 1.0, v43
	v_rcp_f32_e32 v48, v29
	s_waitcnt lgkmcnt(0)
	v_pk_add_f32 v[18:19], v[18:19], v[30:31]
	ds_bpermute_b32 v31, v22, v19
	ds_bpermute_b32 v30, v22, v18
	v_add_f32_e32 v29, 1.0, v49
	v_rcp_f32_e32 v42, v42
	v_rcp_f32_e32 v43, v43
	v_rcp_f32_e32 v49, v29
	s_waitcnt lgkmcnt(0)
	v_pk_add_f32 v[18:19], v[18:19], v[30:31]
	ds_bpermute_b32 v31, v21, v19
	ds_bpermute_b32 v30, v21, v18
	v_pk_mul_f32 v[42:43], v[42:43], v[44:45]
	v_pk_mul_f32 v[44:45], v[48:49], v[46:47]
	v_lshlrev_b32_e32 v46, 16, v28
	v_and_b32_e32 v47, 0xffff0000, v28
	s_waitcnt lgkmcnt(0)
	v_pk_add_f32 v[18:19], v[18:19], v[30:31]
	ds_bpermute_b32 v29, v20, v19
	ds_bpermute_b32 v28, v20, v18
	v_mul_f32_e32 v30, 0xbfb8aa3b, v46
	v_exp_f32_e32 v30, v30
	v_mul_f32_e32 v31, 0xbfb8aa3b, v47
	v_exp_f32_e32 v31, v31
	s_waitcnt lgkmcnt(0)
	v_pk_add_f32 v[18:19], v[18:19], v[28:29]
	v_add_f32_e32 v31, 1.0, v31
	v_pk_mul_f32 v[18:19], v[18:19], s[12:13] op_sel_hi:[1,0]
	s_nop 0
	v_fma_f32 v28, -v19, v19, v18
	v_max_f32_e32 v28, 0, v28
	v_add_f32_e32 v28, 0x3727c5ac, v28
	v_mul_f32_e32 v29, 0x4b800000, v28
	v_cmp_gt_f32_e32 vcc, s94, v28
	v_pk_add_f32 v[36:37], v[36:37], v[18:19] op_sel:[0,1] neg_lo:[0,1] neg_hi:[0,1]
	v_pk_add_f32 v[38:39], v[38:39], v[18:19] op_sel:[0,1] neg_lo:[0,1] neg_hi:[0,1]
	v_cndmask_b32_e32 v28, v28, v29, vcc
	v_rsq_f32_e32 v29, v28
	v_add_f32_e32 v28, 1.0, v30
	v_rcp_f32_e32 v28, v28
	v_pk_add_f32 v[32:33], v[32:33], v[18:19] op_sel:[0,1] neg_lo:[0,1] neg_hi:[0,1]
	v_mul_f32_e32 v30, 0x45800000, v29
	v_cndmask_b32_e32 v30, v29, v30, vcc
	v_pk_mul_f32 v[36:37], v[36:37], v[30:31] op_sel_hi:[1,0]
	v_pk_add_f32 v[18:19], v[34:35], v[18:19] op_sel:[0,1] neg_lo:[0,1] neg_hi:[0,1]
	v_pk_fma_f32 v[36:37], v[8:9], v[36:37], v[12:13]
	v_mul_f32_e32 v34, 0xbfb8aa3b, v40
	v_mul_f32_e32 v29, 0xbfb8aa3b, v36
	v_exp_f32_e32 v48, v29
	v_mul_f32_e32 v29, 0xbfb8aa3b, v37
	v_exp_f32_e32 v49, v29
	v_rcp_f32_e32 v29, v31
	v_add_f32_e32 v31, 1.0, v48
	v_rcp_f32_e32 v48, v31
	v_add_f32_e32 v31, 1.0, v49
	v_pk_mul_f32 v[38:39], v[38:39], v[30:31] op_sel_hi:[1,0]
	v_pk_mul_f32 v[28:29], v[28:29], v[46:47]
	v_pk_fma_f32 v[38:39], v[10:11], v[38:39], v[14:15]
	v_exp_f32_e32 v34, v34
	v_mul_f32_e32 v49, 0xbfb8aa3b, v38
	v_exp_f32_e32 v50, v49
	v_mul_f32_e32 v49, 0xbfb8aa3b, v39
	v_exp_f32_e32 v51, v49
	v_rcp_f32_e32 v49, v31
	v_add_f32_e32 v31, 1.0, v50
	v_rcp_f32_e32 v50, v31
	v_add_f32_e32 v31, 1.0, v51
	v_rcp_f32_e32 v51, v31
	v_pk_mul_f32 v[32:33], v[32:33], v[30:31] op_sel_hi:[1,0]
	v_pk_mul_f32 v[36:37], v[36:37], v[48:49]
	v_pk_fma_f32 v[32:33], v[0:1], v[32:33], v[4:5]
	v_pk_mul_f32 v[28:29], v[28:29], v[36:37]
	v_mul_f32_e32 v31, 0xbfb8aa3b, v32
	v_pk_mul_f32 v[36:37], v[38:39], v[50:51]
	v_exp_f32_e32 v31, v31
	v_mul_f32_e32 v38, 0xbfb8aa3b, v33
	v_exp_f32_e32 v39, v38
	v_pk_mul_f32 v[36:37], v[44:45], v[36:37]
	v_add_f32_e32 v31, 1.0, v31
	v_rcp_f32_e32 v38, v31
	v_add_f32_e32 v31, 1.0, v39
	v_pk_mul_f32 v[18:19], v[18:19], v[30:31] op_sel_hi:[1,0]
	v_rcp_f32_e32 v39, v31
	v_pk_fma_f32 v[18:19], v[2:3], v[18:19], v[6:7]
	v_add_f32_e32 v31, 1.0, v34
	v_mul_f32_e32 v34, 0xbfb8aa3b, v19
	v_mul_f32_e32 v30, 0xbfb8aa3b, v18
	v_exp_f32_e32 v35, v34
	v_mul_f32_e32 v34, 0xbfb8aa3b, v41
	v_exp_f32_e32 v30, v30
	v_exp_f32_e32 v44, v34
	v_rcp_f32_e32 v34, v31
	v_add_f32_e32 v31, 1.0, v35
	v_add_f32_e32 v30, 1.0, v30
	v_add_f32_e32 v35, 1.0, v44
	v_rcp_f32_e32 v30, v30
	v_rcp_f32_e32 v31, v31
	v_rcp_f32_e32 v35, v35
	v_pk_mul_f32 v[32:33], v[32:33], v[38:39]
	v_cvt_pk_bf16_f32 v28, v28, v29
	v_pk_mul_f32 v[18:19], v[18:19], v[30:31]
	v_pk_mul_f32 v[30:31], v[34:35], v[40:41]
	v_pk_mul_f32 v[32:33], v[42:43], v[32:33]
	v_pk_mul_f32 v[18:19], v[30:31], v[18:19]
	v_cvt_pk_bf16_f32 v29, v36, v37
	v_cvt_pk_bf16_f32 v30, v32, v33
	v_cvt_pk_bf16_f32 v31, v18, v19
	global_store_dwordx4 v[16:17], v[28:31], off sc1
	s_nop 1
	v_add_u32_e32 v16, s3, v26
	v_ashrrev_i32_e32 v17, 31, v16
	v_lshlrev_b64 v[16:17], 13, v[16:17]
	v_lshl_add_u64 v[16:17], s[78:79], 0, v[16:17]
	v_lshl_add_u64 v[16:17], v[16:17], 0, v[128:129]
	v_add_co_u32_e32 v18, vcc, s0, v16
	v_mov_b32_e32 v46, v129
	s_nop 0
	v_addc_co_u32_e32 v19, vcc, 0, v17, vcc
	v_mov_b32_e32 v28, v152
	v_mov_b32_e32 v29, v153
	v_mov_b32_e32 v30, v154
	v_mov_b32_e32 v31, v155
	v_lshl_add_u32 v18, v26, 11, v27
	ds_read_b128 v[32:35], v18 offset:63504
	ds_read_b128 v[36:39], v18 offset:63488
	v_readlane_b32 s0, v234, 41
	v_lshl_add_u64 v[16:17], v[16:17], 0, s[10:11]
	s_add_i32 s8, s8, s0
	s_waitcnt lgkmcnt(1)
	v_pk_mul_f32 v[40:41], v[32:33], v[32:33]
	s_waitcnt lgkmcnt(0)
; __device__ __forceinline__ float sigmoidf_(float x) { return __builtin_amdgcn_rcpf(1.0f + __expf(-x)); }
; __device__ __forceinline__ float siluf_(float x) { return x * sigmoidf_(x); }
; __device__ __forceinline__ void conv_item(const Params& p, int l, int item) {
;     ...
; #pragma unroll
;             for (int i = 0; i < 8; ++i) { s += v[i]; ss += v[i] * v[i]; }
;             s = wave_sum(s); ss = wave_sum(ss);
;             const float mean = s * (1.0f / 512.f);
;             const float var = fmaxf(ss * (1.0f / 512.f) - mean * mean, 0.f);
;             const float rstd = rsqrtf(var + 1e-5f);
;             bf16_t* gp = P1 + (long)(R0 + t) * P1W + 2048 + lane * 8;
;             uint4 gv = ld_nt_u4(gp);
;             const float gt[8] = {bflo(gv.x), bfhi(gv.x), bflo(gv.y), bfhi(gv.y), bflo(gv.z), bfhi(gv.z), bflo(gv.w), bfhi(gv.w)};
;             float y[8];
; #pragma unroll
;             for (int i = 0; i < 8; ++i) {
;                 float u = (v[i] - mean) * rstd * gg[i] + bb[i];
;                 y[i] = u * sigmoidf_(u) * siluf_(gt[i]);
;             }
;             uint4 o; o.x = pk2(y[0], y[1]); o.y = pk2(y[2], y[3]); o.z = pk2(y[4], y[5]); o.w = pk2(y[6], y[7]);
;             st16_wt(gp, o);
;         }
;     }
;     __syncthreads();
	v_mov_b32_e32 v47, v37
	v_pk_mul_f32 v[44:45], v[36:37], v[36:37]
	v_pk_add_f32 v[46:47], v[36:37], v[46:47]
	v_pk_mul_f32 v[18:19], v[34:35], v[34:35]
	v_pk_mov_b32 v[46:47], v[44:45], v[46:47] op_sel:[1,0]
	v_mov_b32_e32 v45, v37
	v_pk_add_f32 v[44:45], v[46:47], v[44:45]
	v_mov_b32_e32 v47, v38
	v_readlane_b32 s0, v234, 42
	s_add_i32 s3, s3, s0
	s_cmpk_gt_i32 s8, 0x1ff
	v_lshlrev_b32_e32 v42, 16, v30
	v_and_b32_e32 v43, 0xffff0000, v30
	v_mul_f32_e32 v30, 0xbfb8aa3b, v42
	v_lshlrev_b32_e32 v26, 16, v31
	v_and_b32_e32 v27, 0xffff0000, v31
	v_exp_f32_e32 v48, v30
	v_pk_mul_f32 v[30:31], v[38:39], v[38:39]
	s_nop 0
	v_mov_b32_e32 v46, v30
	v_pk_add_f32 v[44:45], v[44:45], v[46:47]
	v_mov_b32_e32 v30, v31
	v_mov_b32_e32 v31, v39
	v_pk_add_f32 v[30:31], v[44:45], v[30:31]
	v_mov_b32_e32 v44, v40
	v_mov_b32_e32 v45, v32
	v_pk_add_f32 v[30:31], v[30:31], v[44:45]
	v_mov_b32_e32 v40, v41
	v_mov_b32_e32 v41, v33
	v_pk_add_f32 v[30:31], v[30:31], v[40:41]
	v_mov_b32_e32 v40, v18
	v_mov_b32_e32 v41, v34
	v_pk_add_f32 v[30:31], v[30:31], v[40:41]
	v_mov_b32_e32 v18, v19
	v_mov_b32_e32 v19, v35
	v_pk_add_f32 v[18:19], v[30:31], v[18:19]
	ds_bpermute_b32 v31, v25, v19
	ds_bpermute_b32 v30, v25, v18
	v_add_f32_e32 v25, 1.0, v48
	v_rcp_f32_e32 v40, v25
	v_mul_f32_e32 v25, 0xbfb8aa3b, v43
	v_exp_f32_e32 v41, v25
	s_waitcnt lgkmcnt(0)
	v_pk_add_f32 v[18:19], v[18:19], v[30:31]
	ds_bpermute_b32 v25, v24, v19
	ds_bpermute_b32 v24, v24, v18
	v_add_f32_e32 v30, 1.0, v41
	v_rcp_f32_e32 v41, v30
	v_lshlrev_b32_e32 v30, 16, v29
	v_and_b32_e32 v31, 0xffff0000, v29
	s_waitcnt lgkmcnt(0)
	v_pk_add_f32 v[18:19], v[18:19], v[24:25]
	ds_bpermute_b32 v25, v23, v19
	ds_bpermute_b32 v24, v23, v18
	v_mul_f32_e32 v23, 0xbfb8aa3b, v30
	v_exp_f32_e32 v29, v23
	v_mul_f32_e32 v23, 0xbfb8aa3b, v31
	v_exp_f32_e32 v44, v23
	s_waitcnt lgkmcnt(0)
	v_pk_add_f32 v[18:19], v[18:19], v[24:25]
	ds_bpermute_b32 v23, v22, v19
	ds_bpermute_b32 v22, v22, v18
	v_add_f32_e32 v24, 1.0, v29
	v_add_f32_e32 v25, 1.0, v44
	v_rcp_f32_e32 v24, v24
	v_rcp_f32_e32 v25, v25
	s_waitcnt lgkmcnt(0)
	v_pk_add_f32 v[18:19], v[18:19], v[22:23]
	ds_bpermute_b32 v23, v21, v19
	ds_bpermute_b32 v22, v21, v18
	v_pk_mul_f32 v[24:25], v[24:25], v[30:31]
	v_lshlrev_b32_e32 v30, 16, v28
	v_and_b32_e32 v31, 0xffff0000, v28
	v_pk_mul_f32 v[40:41], v[40:41], v[42:43]
	s_waitcnt lgkmcnt(0)
	v_pk_add_f32 v[18:19], v[18:19], v[22:23]
	ds_bpermute_b32 v21, v20, v19
	ds_bpermute_b32 v20, v20, v18
	v_mul_f32_e32 v22, 0xbfb8aa3b, v30
	v_exp_f32_e32 v22, v22
	v_mul_f32_e32 v23, 0xbfb8aa3b, v31
	v_exp_f32_e32 v23, v23
	s_waitcnt lgkmcnt(0)
	v_pk_add_f32 v[18:19], v[18:19], v[20:21]
	v_add_f32_e32 v23, 1.0, v23
	v_pk_mul_f32 v[18:19], v[18:19], s[12:13] op_sel_hi:[1,0]
	s_nop 0
	v_fma_f32 v20, -v19, v19, v18
	v_max_f32_e32 v20, 0, v20
	v_add_f32_e32 v20, 0x3727c5ac, v20
	v_mul_f32_e32 v21, 0x4b800000, v20
	v_cmp_gt_f32_e32 vcc, s94, v20
	v_pk_add_f32 v[28:29], v[36:37], v[18:19] op_sel:[0,1] neg_lo:[0,1] neg_hi:[0,1]
	s_nop 0
	v_cndmask_b32_e32 v20, v20, v21, vcc
	v_rsq_f32_e32 v21, v20
	v_add_f32_e32 v20, 1.0, v22
	v_rcp_f32_e32 v20, v20
	v_mul_f32_e32 v22, 0x45800000, v21
	v_cndmask_b32_e32 v22, v21, v22, vcc
	v_pk_mul_f32 v[28:29], v[28:29], v[22:23] op_sel_hi:[1,0]
	v_rcp_f32_e32 v21, v23
	v_pk_fma_f32 v[8:9], v[8:9], v[28:29], v[12:13]
	v_pk_add_f32 v[28:29], v[38:39], v[18:19] op_sel:[0,1] neg_lo:[0,1] neg_hi:[0,1]
	v_mul_f32_e32 v12, 0xbfb8aa3b, v8
	v_mul_f32_e32 v13, 0xbfb8aa3b, v9
	v_exp_f32_e32 v12, v12
	v_exp_f32_e32 v13, v13
	v_pk_mul_f32 v[28:29], v[28:29], v[22:23] op_sel_hi:[1,0]
	v_pk_mul_f32 v[20:21], v[20:21], v[30:31]
	v_add_f32_e32 v12, 1.0, v12
	v_add_f32_e32 v13, 1.0, v13
	v_rcp_f32_e32 v12, v12
	v_rcp_f32_e32 v13, v13
	v_pk_fma_f32 v[10:11], v[10:11], v[28:29], v[14:15]
	v_pk_mul_f32 v[8:9], v[8:9], v[12:13]
	v_mul_f32_e32 v14, 0xbfb8aa3b, v10
	v_mul_f32_e32 v15, 0xbfb8aa3b, v11
	v_exp_f32_e32 v14, v14
	v_exp_f32_e32 v15, v15
	v_pk_add_f32 v[12:13], v[32:33], v[18:19] op_sel:[0,1] neg_lo:[0,1] neg_hi:[0,1]
	v_pk_mul_f32 v[8:9], v[20:21], v[8:9]
	v_pk_mul_f32 v[12:13], v[12:13], v[22:23] op_sel_hi:[1,0]
	v_add_f32_e32 v14, 1.0, v14
	v_pk_fma_f32 v[0:1], v[0:1], v[12:13], v[4:5]
	v_add_f32_e32 v15, 1.0, v15
	v_mul_f32_e32 v4, 0xbfb8aa3b, v0
	v_rcp_f32_e32 v14, v14
	v_rcp_f32_e32 v15, v15
	v_exp_f32_e32 v12, v4
	v_mul_f32_e32 v4, 0xbfb8aa3b, v1
	v_exp_f32_e32 v13, v4
	v_pk_mul_f32 v[10:11], v[10:11], v[14:15]
	s_nop 0
	v_pk_mul_f32 v[4:5], v[24:25], v[10:11]
	v_add_f32_e32 v10, 1.0, v12
	v_add_f32_e32 v11, 1.0, v13
	v_pk_add_f32 v[12:13], v[34:35], v[18:19] op_sel:[0,1] neg_lo:[0,1] neg_hi:[0,1]
	v_rcp_f32_e32 v10, v10
	v_pk_mul_f32 v[12:13], v[12:13], v[22:23] op_sel_hi:[1,0]
	v_rcp_f32_e32 v11, v11
	v_pk_fma_f32 v[2:3], v[2:3], v[12:13], v[6:7]
	v_mul_f32_e32 v7, 0xbfb8aa3b, v26
	v_mul_f32_e32 v12, 0xbfb8aa3b, v3
	v_mul_f32_e32 v6, 0xbfb8aa3b, v2
	v_exp_f32_e32 v7, v7
	v_exp_f32_e32 v13, v12
	v_mul_f32_e32 v12, 0xbfb8aa3b, v27
	v_exp_f32_e32 v6, v6
	v_exp_f32_e32 v14, v12
	v_add_f32_e32 v7, 1.0, v7
	v_rcp_f32_e32 v12, v7
	v_add_f32_e32 v6, 1.0, v6
	v_add_f32_e32 v7, 1.0, v13
	v_add_f32_e32 v13, 1.0, v14
	v_rcp_f32_e32 v6, v6
	v_rcp_f32_e32 v7, v7
	v_rcp_f32_e32 v13, v13
	v_pk_mul_f32 v[0:1], v[0:1], v[10:11]
	s_nop 0
	v_pk_mul_f32 v[10:11], v[40:41], v[0:1]
	v_pk_mul_f32 v[0:1], v[2:3], v[6:7]
	v_pk_mul_f32 v[2:3], v[12:13], v[26:27]
	s_nop 0
	v_pk_mul_f32 v[6:7], v[2:3], v[0:1]
	v_cvt_pk_bf16_f32 v0, v8, v9
	v_cvt_pk_bf16_f32 v1, v4, v5
	v_cvt_pk_bf16_f32 v2, v10, v11
	v_cvt_pk_bf16_f32 v3, v6, v7
	global_store_dwordx4 v[16:17], v[0:3], off sc1
	s_nop 1
	s_barrier
	s_cbranch_scc1 .LBB0_196
